# v12: GEMM K-loops: setprio moved off the barrier->MFMA and MFMA->barrier paths, redundant lgkmcnt(0) and mid-segment setprio pair dropped
# speedup vs baseline: 1.0408x; 1.0014x over previous
; #define PG8_STAGE(bufoff, gbase, voff) do { _Pragma("unroll") for (int _i = 0; _i < 2; ++_i) \
;         __builtin_amdgcn_global_load_lds((const unsigned*)((const char*)(gbase) + (voff)[_i]), (PG8_LAS unsigned*)(lds + (bufoff) + ldsw + _i * 8192), 16, 0, 0); } while (0)
; #define PG8_LDA(dst, b, h) do { _Pragma("unroll") for (int m = 0; m < 4; ++m) _Pragma("unroll") for (int k = 0; k < 2; ++k) dst[m][k] = *(const PG8_LAS bf16x8*)(lds + PG8_SA(b, h) + aoff + m * 2048 + k * 1024); } while (0)
; #define PG8_LDB(dst, b, h) do { _Pragma("unroll") for (int n = 0; n < 2; ++n) _Pragma("unroll") for (int k = 0; k < 2; ++k) dst[n][k] = *(const PG8_LAS bf16x8*)(lds + PG8_SB(b, h) + boff + n * 2048 + k * 1024); } while (0)
; #define PG8_WAIT_V(n) asm volatile("s_waitcnt vmcnt(" #n ")" ::: "memory")
; #define PG8_WAIT_L(n) asm volatile("s_waitcnt lgkmcnt(" #n ")" ::: "memory")
; #define PG8_BAR __builtin_amdgcn_s_barrier()
; #define PG8_SCHED __builtin_amdgcn_sched_barrier(0)
; template <class Epi, class Sched, bool ALIGN_EPI = false, bool SP2 = false, bool I8 = false, bool F16 = false>
; __device__ __forceinline__ void gemm_phase(PG8_LAS unsigned char* lds, const Gemm g, const Sched& S, const Epi& E) {
;     ...
;             PG8_LDB(B0, 0, 0); PG8_LDB(B1, 0, 1); PG8_SCHED; PG8_LDA(At, 0, 0); PG8_STAGE(PG8_SA(1, 1), a1 + hstep, voffA);
;             PG8_WAIT_V(8); PG8_WAIT_L(0); PG8_BAR; PG8_MMA(0, 0, At, B0); PG8_MMA(0, 1, At, B1); PG8_BAR; PG8_SCHED;
;             PG8_LDA(At, 0, 1); PG8_STAGE(PG8_SB(0, 0), b2, voffB); PG8_STAGE(PG8_SB(0, 1), b2 + hstep, voffB); PG8_STAGE(PG8_SA(0, 0), a2, voffA);
;             PG8_WAIT_V(8); PG8_WAIT_L(0); PG8_BAR; PG8_MMA(1, 0, At, B0); PG8_MMA(1, 1, At, B1); PG8_BAR; PG8_SCHED;
.LBB0_300:
	s_add_u32 s30, s6, 0xfff00080
	s_addc_u32 s31, s7, -1
	s_add_i32 s85, 0, 0x10000
	s_cmp_eq_u32 s83, 60
	s_cselect_b32 s55, s45, s31
	s_cselect_b32 s54, s70, s30
	v_add_u32_e32 v150, s85, v152
	s_cselect_b32 s53, s37, s81
	s_cselect_b32 s52, s71, s79
	s_add_i32 vcc_lo, 0, 0x14000
	ds_read_b128 v[142:145], v150
	ds_read_b128 v[146:149], v150 offset:1024
	ds_read_b128 v[156:159], v150 offset:2048
	ds_read_b128 v[160:163], v150 offset:3072
	v_add_u32_e32 v150, vcc_lo, v152
	ds_read_b128 v[164:167], v150
	ds_read_b128 v[168:171], v150 offset:1024
	ds_read_b128 v[172:175], v150 offset:2048
	ds_read_b128 v[176:179], v150 offset:3072
	v_lshl_add_u64 v[150:151], s[6:7], 0, v[138:139]
	s_add_i32 m0, s57, 0xc000
	ds_read_b128 v[198:201], v154
	ds_read_b128 v[202:205], v154 offset:1024
	ds_read_b128 v[206:209], v154 offset:2048
	s_waitcnt vmcnt(0)
	ds_read_b128 v[226:229], v154 offset:3072
	ds_read_b128 v[230:233], v154 offset:4096
	ds_read_b128 v[234:237], v154 offset:5120
	ds_read_b128 v[238:241], v154 offset:6144
	ds_read_b128 v[242:245], v154 offset:7168
	global_load_lds_dwordx4 v[150:151], off
	v_lshl_add_u64 v[150:151], s[6:7], 0, v[140:141]
	s_add_i32 m0, s57, 0xe000
	s_nop 0
	global_load_lds_dwordx4 v[150:151], off
	s_waitcnt vmcnt(8)
	s_waitcnt lgkmcnt(0)
	s_setprio 1
	s_barrier
	v_mfma_f32_16x16x32_f16 v[126:129], v[142:145], v[198:201], v[126:129]
	v_mfma_f32_16x16x32_f16 v[122:125], v[156:159], v[198:201], v[122:125]
	v_mfma_f32_16x16x32_f16 v[110:113], v[142:145], v[206:209], v[110:113]
	v_mfma_f32_16x16x32_f16 v[106:109], v[156:159], v[206:209], v[106:109]
	v_mfma_f32_16x16x32_f16 v[94:97], v[142:145], v[230:233], v[94:97]
	v_mfma_f32_16x16x32_f16 v[90:93], v[156:159], v[230:233], v[90:93]
	v_mfma_f32_16x16x32_f16 v[78:81], v[142:145], v[238:241], v[78:81]
	v_mfma_f32_16x16x32_f16 v[74:77], v[156:159], v[238:241], v[74:77]
	v_mfma_f32_16x16x32_f16 v[126:129], v[146:149], v[202:205], v[126:129]
	v_mfma_f32_16x16x32_f16 v[122:125], v[160:163], v[202:205], v[122:125]
	v_mfma_f32_16x16x32_f16 v[110:113], v[146:149], v[226:229], v[110:113]
	v_mfma_f32_16x16x32_f16 v[106:109], v[160:163], v[226:229], v[106:109]
	v_mfma_f32_16x16x32_f16 v[94:97], v[146:149], v[234:237], v[94:97]
	v_mfma_f32_16x16x32_f16 v[90:93], v[160:163], v[234:237], v[90:93]
	v_mfma_f32_16x16x32_f16 v[78:81], v[146:149], v[242:245], v[78:81]
	v_mfma_f32_16x16x32_f16 v[74:77], v[160:163], v[242:245], v[74:77]
	v_mfma_f32_16x16x32_f16 v[118:121], v[164:167], v[198:201], v[118:121]
	v_mfma_f32_16x16x32_f16 v[114:117], v[172:175], v[198:201], v[114:117]
	v_mfma_f32_16x16x32_f16 v[102:105], v[164:167], v[206:209], v[102:105]
	v_mfma_f32_16x16x32_f16 v[98:101], v[172:175], v[206:209], v[98:101]
	v_mfma_f32_16x16x32_f16 v[86:89], v[164:167], v[230:233], v[86:89]
	v_mfma_f32_16x16x32_f16 v[82:85], v[172:175], v[230:233], v[82:85]
	v_mfma_f32_16x16x32_f16 v[70:73], v[164:167], v[238:241], v[70:73]
	v_mfma_f32_16x16x32_f16 v[66:69], v[172:175], v[238:241], v[66:69]
	v_mfma_f32_16x16x32_f16 v[118:121], v[168:171], v[202:205], v[118:121]
	v_mfma_f32_16x16x32_f16 v[114:117], v[176:179], v[202:205], v[114:117]
	v_mfma_f32_16x16x32_f16 v[102:105], v[168:171], v[226:229], v[102:105]
	v_mfma_f32_16x16x32_f16 v[98:101], v[176:179], v[226:229], v[98:101]
	v_mfma_f32_16x16x32_f16 v[86:89], v[168:171], v[234:237], v[86:89]
	v_mfma_f32_16x16x32_f16 v[82:85], v[176:179], v[234:237], v[82:85]
	v_mfma_f32_16x16x32_f16 v[70:73], v[168:171], v[242:245], v[70:73]
	v_mfma_f32_16x16x32_f16 v[66:69], v[176:179], v[242:245], v[66:69]
	s_barrier
	s_setprio 0
	s_add_i32 s30, s85, s56
	v_lshl_add_u64 v[150:151], s[52:53], 0, v[182:183]
	s_mov_b32 m0, s30
	ds_read_b128 v[198:201], v154 offset:16384
	ds_read_b128 v[202:205], v154 offset:17408
	ds_read_b128 v[206:209], v154 offset:18432
	ds_read_b128 v[226:229], v154 offset:19456
	ds_read_b128 v[230:233], v154 offset:20480
	ds_read_b128 v[234:237], v154 offset:21504
	ds_read_b128 v[238:241], v154 offset:22528
	ds_read_b128 v[242:245], v154 offset:23552
	global_load_lds_dwordx4 v[150:151], off
	s_add_i32 m0, s30, 0x2000
	s_add_u32 s30, s52, 0x100000
	v_lshl_add_u64 v[180:181], s[52:53], 0, v[130:131]
	s_addc_u32 s31, s53, 0
	s_add_i32 s85, vcc_lo, s56
	global_load_lds_dwordx4 v[180:181], off
	v_lshl_add_u64 v[210:211], s[30:31], 0, v[182:183]
	s_mov_b32 m0, s85
	v_lshl_add_u64 v[246:247], s[54:55], 0, v[132:133]
	global_load_lds_dwordx4 v[210:211], off
	v_lshl_add_u64 v[210:211], s[30:31], 0, v[130:131]
	s_add_i32 m0, s85, 0x2000
	s_nop 0
	global_load_lds_dwordx4 v[210:211], off
	v_lshl_add_u64 v[210:211], s[54:55], 0, v[134:135]
	s_mov_b32 m0, s57
	s_nop 0
	global_load_lds_dwordx4 v[210:211], off
	s_mov_b32 m0, s58
	s_nop 0
	global_load_lds_dwordx4 v[246:247], off
	s_waitcnt vmcnt(8)
	s_waitcnt lgkmcnt(0)
	s_setprio 1
	s_barrier
; #define PG8_STAGE(bufoff, gbase, voff) do { _Pragma("unroll") for (int _i = 0; _i < 2; ++_i) \
;         __builtin_amdgcn_global_load_lds((const unsigned*)((const char*)(gbase) + (voff)[_i]), (PG8_LAS unsigned*)(lds + (bufoff) + ldsw + _i * 8192), 16, 0, 0); } while (0)
; #define PG8_LDA(dst, b, h) do { _Pragma("unroll") for (int m = 0; m < 4; ++m) _Pragma("unroll") for (int k = 0; k < 2; ++k) dst[m][k] = *(const PG8_LAS bf16x8*)(lds + PG8_SA(b, h) + aoff + m * 2048 + k * 1024); } while (0)
; #define PG8_LDB(dst, b, h) do { _Pragma("unroll") for (int n = 0; n < 2; ++n) _Pragma("unroll") for (int k = 0; k < 2; ++k) dst[n][k] = *(const PG8_LAS bf16x8*)(lds + PG8_SB(b, h) + boff + n * 2048 + k * 1024); } while (0)
; #define PG8_WAIT_V(n) asm volatile("s_waitcnt vmcnt(" #n ")" ::: "memory")
; #define PG8_WAIT_L(n) asm volatile("s_waitcnt lgkmcnt(" #n ")" ::: "memory")
; #define PG8_BAR __builtin_amdgcn_s_barrier()
; #define PG8_SCHED __builtin_amdgcn_sched_barrier(0)
; template <class Epi, class Sched, bool ALIGN_EPI = false, bool SP2 = false, bool I8 = false, bool F16 = false>
; __device__ __forceinline__ void gemm_phase(PG8_LAS unsigned char* lds, const Gemm g, const Sched& S, const Epi& E) {
;     ...
;             PG8_WAIT_V(8); PG8_WAIT_L(0); PG8_BAR; PG8_MMA(0, 0, At, B0); PG8_MMA(0, 1, At, B1); PG8_BAR; PG8_SCHED;
;             PG8_LDA(At, 0, 1); PG8_STAGE(PG8_SB(0, 0), b2, voffB); PG8_STAGE(PG8_SB(0, 1), b2 + hstep, voffB); PG8_STAGE(PG8_SA(0, 0), a2, voffA);
;             PG8_WAIT_V(8); PG8_WAIT_L(0); PG8_BAR; PG8_MMA(1, 0, At, B0); PG8_MMA(1, 1, At, B1); PG8_BAR; PG8_SCHED;
;             PG8_LDB(B0, 1, 0); PG8_LDB(B1, 1, 1); PG8_SCHED; PG8_LDA(At, 1, 0); PG8_STAGE(PG8_SA(0, 1), a2 + hstep, voffA);
;             PG8_WAIT_V(8); PG8_WAIT_L(0); PG8_BAR; PG8_MMA(0, 0, At, B0); PG8_MMA(0, 1, At, B1); PG8_BAR; PG8_SCHED;
	v_mfma_f32_16x16x32_f16 v[62:65], v[142:145], v[198:201], v[62:65]
	v_mfma_f32_16x16x32_f16 v[58:61], v[156:159], v[198:201], v[58:61]
	v_mfma_f32_16x16x32_f16 v[46:49], v[142:145], v[206:209], v[46:49]
	v_mfma_f32_16x16x32_f16 v[42:45], v[156:159], v[206:209], v[42:45]
	v_mfma_f32_16x16x32_f16 v[30:33], v[142:145], v[230:233], v[30:33]
	v_mfma_f32_16x16x32_f16 v[26:29], v[156:159], v[230:233], v[26:29]
	v_mfma_f32_16x16x32_f16 v[14:17], v[142:145], v[238:241], v[14:17]
	v_mfma_f32_16x16x32_f16 v[10:13], v[156:159], v[238:241], v[10:13]
	v_mfma_f32_16x16x32_f16 v[62:65], v[146:149], v[202:205], v[62:65]
	v_mfma_f32_16x16x32_f16 v[58:61], v[160:163], v[202:205], v[58:61]
	v_mfma_f32_16x16x32_f16 v[46:49], v[146:149], v[226:229], v[46:49]
	v_mfma_f32_16x16x32_f16 v[42:45], v[160:163], v[226:229], v[42:45]
	v_mfma_f32_16x16x32_f16 v[30:33], v[146:149], v[234:237], v[30:33]
	v_mfma_f32_16x16x32_f16 v[26:29], v[160:163], v[234:237], v[26:29]
	v_mfma_f32_16x16x32_f16 v[14:17], v[146:149], v[242:245], v[14:17]
	v_mfma_f32_16x16x32_f16 v[10:13], v[160:163], v[242:245], v[10:13]
	v_mfma_f32_16x16x32_f16 v[54:57], v[164:167], v[198:201], v[54:57]
	v_mfma_f32_16x16x32_f16 v[50:53], v[172:175], v[198:201], v[50:53]
	v_mfma_f32_16x16x32_f16 v[38:41], v[164:167], v[206:209], v[38:41]
	v_mfma_f32_16x16x32_f16 v[34:37], v[172:175], v[206:209], v[34:37]
	v_mfma_f32_16x16x32_f16 v[22:25], v[164:167], v[230:233], v[22:25]
	v_mfma_f32_16x16x32_f16 v[18:21], v[172:175], v[230:233], v[18:21]
	v_mfma_f32_16x16x32_f16 v[6:9], v[164:167], v[238:241], v[6:9]
	v_mfma_f32_16x16x32_f16 v[2:5], v[172:175], v[238:241], v[2:5]
	v_mfma_f32_16x16x32_f16 v[54:57], v[168:171], v[202:205], v[54:57]
	v_mfma_f32_16x16x32_f16 v[50:53], v[176:179], v[202:205], v[50:53]
	v_mfma_f32_16x16x32_f16 v[38:41], v[168:171], v[226:229], v[38:41]
	v_mfma_f32_16x16x32_f16 v[34:37], v[176:179], v[226:229], v[34:37]
	v_mfma_f32_16x16x32_f16 v[22:25], v[168:171], v[234:237], v[22:25]
	v_mfma_f32_16x16x32_f16 v[18:21], v[176:179], v[234:237], v[18:21]
	v_mfma_f32_16x16x32_f16 v[6:9], v[168:171], v[242:245], v[6:9]
	v_mfma_f32_16x16x32_f16 v[2:5], v[176:179], v[242:245], v[2:5]
	s_barrier
	s_setprio 0
	s_add_i32 s85, 0, 0x18000
	v_add_u32_e32 v155, s85, v152
	s_add_i32 vcc_lo, 0, 0x1c000
	ds_read_b128 v[142:145], v155
	ds_read_b128 v[146:149], v155 offset:1024
	ds_read_b128 v[156:159], v155 offset:2048
	ds_read_b128 v[160:163], v155 offset:3072
	v_add_u32_e32 v155, vcc_lo, v152
	ds_read_b128 v[164:167], v155
	ds_read_b128 v[168:171], v155 offset:1024
	ds_read_b128 v[172:175], v155 offset:2048
	ds_read_b128 v[176:179], v155 offset:3072
	s_add_u32 s30, s54, 0x100000
	s_addc_u32 s31, s55, 0
	s_mov_b32 m0, s59
	v_lshl_add_u64 v[248:249], s[30:31], 0, v[134:135]
	ds_read_b128 v[198:201], v154 offset:32768
	ds_read_b128 v[202:205], v154 offset:33792
	ds_read_b128 v[206:209], v154 offset:34816
	ds_read_b128 v[226:229], v154 offset:35840
	ds_read_b128 v[230:233], v154 offset:36864
	ds_read_b128 v[234:237], v154 offset:37888
	ds_read_b128 v[238:241], v154 offset:38912
	ds_read_b128 v[242:245], v154 offset:39936
	global_load_lds_dwordx4 v[248:249], off
	v_lshl_add_u64 v[248:249], s[30:31], 0, v[132:133]
	s_mov_b32 m0, s62
	s_nop 0
	global_load_lds_dwordx4 v[248:249], off
	s_waitcnt vmcnt(8)
	s_waitcnt lgkmcnt(0)
	s_setprio 1
	s_barrier
	v_mfma_f32_16x16x32_f16 v[126:129], v[142:145], v[198:201], v[126:129]
	v_mfma_f32_16x16x32_f16 v[122:125], v[156:159], v[198:201], v[122:125]
	v_mfma_f32_16x16x32_f16 v[110:113], v[142:145], v[206:209], v[110:113]
	v_mfma_f32_16x16x32_f16 v[106:109], v[156:159], v[206:209], v[106:109]
	v_mfma_f32_16x16x32_f16 v[94:97], v[142:145], v[230:233], v[94:97]
	v_mfma_f32_16x16x32_f16 v[90:93], v[156:159], v[230:233], v[90:93]
	v_mfma_f32_16x16x32_f16 v[78:81], v[142:145], v[238:241], v[78:81]
	v_mfma_f32_16x16x32_f16 v[74:77], v[156:159], v[238:241], v[74:77]
	v_mfma_f32_16x16x32_f16 v[126:129], v[146:149], v[202:205], v[126:129]
	v_mfma_f32_16x16x32_f16 v[122:125], v[160:163], v[202:205], v[122:125]
	v_mfma_f32_16x16x32_f16 v[110:113], v[146:149], v[226:229], v[110:113]
	v_mfma_f32_16x16x32_f16 v[106:109], v[160:163], v[226:229], v[106:109]
	v_mfma_f32_16x16x32_f16 v[94:97], v[146:149], v[234:237], v[94:97]
	v_mfma_f32_16x16x32_f16 v[90:93], v[160:163], v[234:237], v[90:93]
	v_mfma_f32_16x16x32_f16 v[78:81], v[146:149], v[242:245], v[78:81]
	v_mfma_f32_16x16x32_f16 v[74:77], v[160:163], v[242:245], v[74:77]
	v_mfma_f32_16x16x32_f16 v[118:121], v[164:167], v[198:201], v[118:121]
	v_mfma_f32_16x16x32_f16 v[114:117], v[172:175], v[198:201], v[114:117]
	v_mfma_f32_16x16x32_f16 v[102:105], v[164:167], v[206:209], v[102:105]
	v_mfma_f32_16x16x32_f16 v[98:101], v[172:175], v[206:209], v[98:101]
	v_mfma_f32_16x16x32_f16 v[86:89], v[164:167], v[230:233], v[86:89]
	v_mfma_f32_16x16x32_f16 v[82:85], v[172:175], v[230:233], v[82:85]
	v_mfma_f32_16x16x32_f16 v[70:73], v[164:167], v[238:241], v[70:73]
	v_mfma_f32_16x16x32_f16 v[66:69], v[172:175], v[238:241], v[66:69]
	v_mfma_f32_16x16x32_f16 v[118:121], v[168:171], v[202:205], v[118:121]
	v_mfma_f32_16x16x32_f16 v[114:117], v[176:179], v[202:205], v[114:117]
	v_mfma_f32_16x16x32_f16 v[102:105], v[168:171], v[226:229], v[102:105]
	v_mfma_f32_16x16x32_f16 v[98:101], v[176:179], v[226:229], v[98:101]
	v_mfma_f32_16x16x32_f16 v[86:89], v[168:171], v[234:237], v[86:89]
	v_mfma_f32_16x16x32_f16 v[82:85], v[176:179], v[234:237], v[82:85]
	v_mfma_f32_16x16x32_f16 v[70:73], v[168:171], v[242:245], v[70:73]
	v_mfma_f32_16x16x32_f16 v[66:69], v[176:179], v[242:245], v[66:69]
	s_barrier
; #define PG8_STAGE(bufoff, gbase, voff) do { _Pragma("unroll") for (int _i = 0; _i < 2; ++_i) \
;         __builtin_amdgcn_global_load_lds((const unsigned*)((const char*)(gbase) + (voff)[_i]), (PG8_LAS unsigned*)(lds + (bufoff) + ldsw + _i * 8192), 16, 0, 0); } while (0)
; #define PG8_LDA(dst, b, h) do { _Pragma("unroll") for (int m = 0; m < 4; ++m) _Pragma("unroll") for (int k = 0; k < 2; ++k) dst[m][k] = *(const PG8_LAS bf16x8*)(lds + PG8_SA(b, h) + aoff + m * 2048 + k * 1024); } while (0)
; #define PG8_WAIT_V(n) asm volatile("s_waitcnt vmcnt(" #n ")" ::: "memory")
; #define PG8_WAIT_L(n) asm volatile("s_waitcnt lgkmcnt(" #n ")" ::: "memory")
; #define PG8_BAR __builtin_amdgcn_s_barrier()
; #define PG8_SCHED __builtin_amdgcn_sched_barrier(0)
; template <class Epi, class Sched, bool ALIGN_EPI = false, bool SP2 = false, bool I8 = false, bool F16 = false>
; __device__ __forceinline__ void gemm_phase(PG8_LAS unsigned char* lds, const Gemm g, const Sched& S, const Epi& E) {
;     ...
;             PG8_WAIT_V(8); PG8_WAIT_L(0); PG8_BAR; PG8_MMA(0, 0, At, B0); PG8_MMA(0, 1, At, B1); PG8_BAR; PG8_SCHED;
;             PG8_LDA(At, 1, 1); PG8_STAGE(PG8_SB(1, 0), b3, voffB); PG8_STAGE(PG8_SB(1, 1), b3 + hstep, voffB); PG8_STAGE(PG8_SA(1, 0), a3, voffA);
;             PG8_WAIT_V(8); PG8_WAIT_L(0); PG8_BAR; PG8_MMA(1, 0, At, B0); PG8_MMA(1, 1, At, B1); PG8_BAR; PG8_SCHED;
	s_setprio 0
	s_add_i32 s30, s85, s56
	v_lshl_add_u64 v[150:151], v[150:151], 0, s[74:75]
	s_mov_b32 m0, s30
	ds_read_b128 v[198:201], v154 offset:49152
	ds_read_b128 v[202:205], v154 offset:50176
	ds_read_b128 v[206:209], v154 offset:51200
	ds_read_b128 v[226:229], v154 offset:52224
	ds_read_b128 v[230:233], v154 offset:53248
	ds_read_b128 v[234:237], v154 offset:54272
	ds_read_b128 v[238:241], v154 offset:55296
	ds_read_b128 v[242:245], v154 offset:56320
	global_load_lds_dwordx4 v[150:151], off
	s_add_i32 m0, s30, 0x2000
	s_add_u32 s30, s52, 0x100080
	v_lshl_add_u64 v[150:151], v[180:181], 0, s[74:75]
	s_addc_u32 s31, s53, 0
	s_add_i32 s52, vcc_lo, s56
	global_load_lds_dwordx4 v[150:151], off
	v_lshl_add_u64 v[150:151], s[30:31], 0, v[182:183]
	s_mov_b32 m0, s52
	s_nop 0
	global_load_lds_dwordx4 v[150:151], off
	v_lshl_add_u64 v[150:151], s[30:31], 0, v[130:131]
	s_add_i32 m0, s52, 0x2000
	s_nop 0
	global_load_lds_dwordx4 v[150:151], off
	v_lshl_add_u64 v[150:151], v[210:211], 0, s[74:75]
	s_mov_b32 m0, s64
	s_nop 0
	global_load_lds_dwordx4 v[150:151], off
	v_lshl_add_u64 v[150:151], v[246:247], 0, s[74:75]
	s_mov_b32 m0, s65
	s_nop 0
	global_load_lds_dwordx4 v[150:151], off
	s_waitcnt vmcnt(8)
	s_waitcnt lgkmcnt(0)
	s_setprio 1
	s_barrier
	v_mfma_f32_16x16x32_f16 v[62:65], v[142:145], v[198:201], v[62:65]
	v_mfma_f32_16x16x32_f16 v[58:61], v[156:159], v[198:201], v[58:61]
	v_mfma_f32_16x16x32_f16 v[46:49], v[142:145], v[206:209], v[46:49]
	v_mfma_f32_16x16x32_f16 v[42:45], v[156:159], v[206:209], v[42:45]
	v_mfma_f32_16x16x32_f16 v[30:33], v[142:145], v[230:233], v[30:33]
	v_mfma_f32_16x16x32_f16 v[26:29], v[156:159], v[230:233], v[26:29]
	v_mfma_f32_16x16x32_f16 v[14:17], v[142:145], v[238:241], v[14:17]
	v_mfma_f32_16x16x32_f16 v[10:13], v[156:159], v[238:241], v[10:13]
	v_mfma_f32_16x16x32_f16 v[62:65], v[146:149], v[202:205], v[62:65]
	v_mfma_f32_16x16x32_f16 v[58:61], v[160:163], v[202:205], v[58:61]
	v_mfma_f32_16x16x32_f16 v[46:49], v[146:149], v[226:229], v[46:49]
	v_mfma_f32_16x16x32_f16 v[42:45], v[160:163], v[226:229], v[42:45]
	v_mfma_f32_16x16x32_f16 v[30:33], v[146:149], v[234:237], v[30:33]
	v_mfma_f32_16x16x32_f16 v[26:29], v[160:163], v[234:237], v[26:29]
	v_mfma_f32_16x16x32_f16 v[14:17], v[146:149], v[242:245], v[14:17]
	v_mfma_f32_16x16x32_f16 v[10:13], v[160:163], v[242:245], v[10:13]
	v_mfma_f32_16x16x32_f16 v[54:57], v[164:167], v[198:201], v[54:57]
	v_mfma_f32_16x16x32_f16 v[50:53], v[172:175], v[198:201], v[50:53]
	v_mfma_f32_16x16x32_f16 v[38:41], v[164:167], v[206:209], v[38:41]
	v_mfma_f32_16x16x32_f16 v[34:37], v[172:175], v[206:209], v[34:37]
	v_mfma_f32_16x16x32_f16 v[22:25], v[164:167], v[230:233], v[22:25]
	v_mfma_f32_16x16x32_f16 v[18:21], v[172:175], v[230:233], v[18:21]
	v_mfma_f32_16x16x32_f16 v[6:9], v[164:167], v[238:241], v[6:9]
	v_mfma_f32_16x16x32_f16 v[2:5], v[172:175], v[238:241], v[2:5]
	v_mfma_f32_16x16x32_f16 v[54:57], v[168:171], v[202:205], v[54:57]
	v_mfma_f32_16x16x32_f16 v[50:53], v[176:179], v[202:205], v[50:53]
	v_mfma_f32_16x16x32_f16 v[38:41], v[168:171], v[226:229], v[38:41]
	v_mfma_f32_16x16x32_f16 v[34:37], v[176:179], v[226:229], v[34:37]
	v_mfma_f32_16x16x32_f16 v[22:25], v[168:171], v[234:237], v[22:25]
	v_mfma_f32_16x16x32_f16 v[18:21], v[176:179], v[234:237], v[18:21]
	v_mfma_f32_16x16x32_f16 v[6:9], v[168:171], v[242:245], v[6:9]
	v_mfma_f32_16x16x32_f16 v[2:5], v[176:179], v[242:245], v[2:5]
	s_barrier
	s_setprio 0
	s_add_i32 s83, s83, 2
	s_add_u32 s6, s6, 0x100
	s_addc_u32 s7, s7, 0
	s_add_u32 s79, s79, 0x100
	s_addc_u32 s81, s81, 0
	s_cmp_gt_u32 s83, 61
	s_cbranch_scc0 .LBB0_300
	s_and_b64 vcc, exec, s[14:15]
	s_cbranch_vccz .LBB0_303
	s_barrier

; #define PG8_STAGE(bufoff, gbase, voff) do { _Pragma("unroll") for (int _i = 0; _i < 2; ++_i) \
;         __builtin_amdgcn_global_load_lds((const unsigned*)((const char*)(gbase) + (voff)[_i]), (PG8_LAS unsigned*)(lds + (bufoff) + ldsw + _i * 8192), 16, 0, 0); } while (0)
; #define PG8_LDA(dst, b, h) do { _Pragma("unroll") for (int m = 0; m < 4; ++m) _Pragma("unroll") for (int k = 0; k < 2; ++k) dst[m][k] = *(const PG8_LAS bf16x8*)(lds + PG8_SA(b, h) + aoff + m * 2048 + k * 1024); } while (0)
; #define PG8_LDB(dst, b, h) do { _Pragma("unroll") for (int n = 0; n < 2; ++n) _Pragma("unroll") for (int k = 0; k < 2; ++k) dst[n][k] = *(const PG8_LAS bf16x8*)(lds + PG8_SB(b, h) + boff + n * 2048 + k * 1024); } while (0)
; #define PG8_WAIT_V(n) asm volatile("s_waitcnt vmcnt(" #n ")" ::: "memory")
; #define PG8_WAIT_L(n) asm volatile("s_waitcnt lgkmcnt(" #n ")" ::: "memory")
; #define PG8_BAR __builtin_amdgcn_s_barrier()
; #define PG8_SCHED __builtin_amdgcn_sched_barrier(0)
; template <class Epi, class Sched, bool ALIGN_EPI = false, bool SP2 = false, bool I8 = false, bool F16 = false>
; __device__ __forceinline__ void gemm_phase(PG8_LAS unsigned char* lds, const Gemm g, const Sched& S, const Epi& E) {
;     ...
;             PG8_LDB(B0, 0, 0); PG8_LDB(B1, 0, 1); PG8_SCHED; PG8_LDA(At, 0, 0); PG8_STAGE(PG8_SA(1, 1), a1 + hstep, voffA);
;             PG8_WAIT_V(8); PG8_WAIT_L(0); PG8_BAR; PG8_MMA(0, 0, At, B0); PG8_MMA(0, 1, At, B1); PG8_BAR; PG8_SCHED;
;             PG8_LDA(At, 0, 1); PG8_STAGE(PG8_SB(0, 0), b2, voffB); PG8_STAGE(PG8_SB(0, 1), b2 + hstep, voffB); PG8_STAGE(PG8_SA(0, 0), a2, voffA);
;             PG8_WAIT_V(8); PG8_WAIT_L(0); PG8_BAR; PG8_MMA(1, 0, At, B0); PG8_MMA(1, 1, At, B1); PG8_BAR; PG8_SCHED;
.LBB0_332:
	s_add_u32 s30, s6, 0xfff80080
	s_addc_u32 s31, s7, -1
	s_add_i32 s85, 0, 0x10000
	s_cmp_eq_u32 s83, 28
	s_cselect_b32 s55, s45, s31
	s_cselect_b32 s54, s70, s30
	s_cselect_b32 s53, s43, s81
	s_cselect_b32 s52, s71, s79
	s_add_i32 vcc_lo, 0, 0x14000
	v_add_u32_e32 v154, s85, v174
	v_add_u32_e32 v170, vcc_lo, v174
	ds_read_b128 v[142:145], v154
	ds_read_b128 v[146:149], v154 offset:1024
	ds_read_b128 v[150:153], v154 offset:2048
	ds_read_b128 v[154:157], v154 offset:3072
	ds_read_b128 v[158:161], v170
	ds_read_b128 v[162:165], v170 offset:1024
	ds_read_b128 v[166:169], v170 offset:2048
	ds_read_b128 v[170:173], v170 offset:3072
	v_lshl_add_u64 v[210:211], s[6:7], 0, v[138:139]
	s_add_i32 m0, s57, 0xc000
	ds_read_b128 v[178:181], v176
	ds_read_b128 v[198:201], v176 offset:1024
	ds_read_b128 v[202:205], v176 offset:2048
	ds_read_b128 v[206:209], v176 offset:3072
	s_waitcnt vmcnt(0)
	ds_read_b128 v[226:229], v176 offset:4096
	ds_read_b128 v[230:233], v176 offset:5120
	ds_read_b128 v[234:237], v176 offset:6144
	ds_read_b128 v[238:241], v176 offset:7168
	global_load_lds_dwordx4 v[210:211], off
	v_lshl_add_u64 v[210:211], s[6:7], 0, v[140:141]
	s_add_i32 m0, s57, 0xe000
	s_nop 0
	global_load_lds_dwordx4 v[210:211], off
	s_waitcnt vmcnt(8)
	s_waitcnt lgkmcnt(0)
	s_setprio 1
	s_barrier
	v_mfma_i32_16x16x64_i8 v[126:129], v[142:145], v[178:181], v[126:129]
	v_mfma_i32_16x16x64_i8 v[122:125], v[150:153], v[178:181], v[122:125]
	v_mfma_i32_16x16x64_i8 v[110:113], v[142:145], v[202:205], v[110:113]
	v_mfma_i32_16x16x64_i8 v[106:109], v[150:153], v[202:205], v[106:109]
	v_mfma_i32_16x16x64_i8 v[94:97], v[142:145], v[226:229], v[94:97]
	v_mfma_i32_16x16x64_i8 v[90:93], v[150:153], v[226:229], v[90:93]
	v_mfma_i32_16x16x64_i8 v[78:81], v[142:145], v[234:237], v[78:81]
	v_mfma_i32_16x16x64_i8 v[74:77], v[150:153], v[234:237], v[74:77]
	v_mfma_i32_16x16x64_i8 v[126:129], v[146:149], v[198:201], v[126:129]
	v_mfma_i32_16x16x64_i8 v[122:125], v[154:157], v[198:201], v[122:125]
	v_mfma_i32_16x16x64_i8 v[110:113], v[146:149], v[206:209], v[110:113]
	v_mfma_i32_16x16x64_i8 v[106:109], v[154:157], v[206:209], v[106:109]
	v_mfma_i32_16x16x64_i8 v[94:97], v[146:149], v[230:233], v[94:97]
	v_mfma_i32_16x16x64_i8 v[90:93], v[154:157], v[230:233], v[90:93]
	v_mfma_i32_16x16x64_i8 v[78:81], v[146:149], v[238:241], v[78:81]
	v_mfma_i32_16x16x64_i8 v[74:77], v[154:157], v[238:241], v[74:77]
	v_mfma_i32_16x16x64_i8 v[118:121], v[158:161], v[178:181], v[118:121]
	v_mfma_i32_16x16x64_i8 v[114:117], v[166:169], v[178:181], v[114:117]
	v_mfma_i32_16x16x64_i8 v[102:105], v[158:161], v[202:205], v[102:105]
	v_mfma_i32_16x16x64_i8 v[98:101], v[166:169], v[202:205], v[98:101]
	v_mfma_i32_16x16x64_i8 v[86:89], v[158:161], v[226:229], v[86:89]
	v_mfma_i32_16x16x64_i8 v[82:85], v[166:169], v[226:229], v[82:85]
	v_mfma_i32_16x16x64_i8 v[70:73], v[158:161], v[234:237], v[70:73]
	v_mfma_i32_16x16x64_i8 v[66:69], v[166:169], v[234:237], v[66:69]
	v_mfma_i32_16x16x64_i8 v[118:121], v[162:165], v[198:201], v[118:121]
	v_mfma_i32_16x16x64_i8 v[114:117], v[170:173], v[198:201], v[114:117]
	v_mfma_i32_16x16x64_i8 v[102:105], v[162:165], v[206:209], v[102:105]
	v_mfma_i32_16x16x64_i8 v[98:101], v[170:173], v[206:209], v[98:101]
	v_mfma_i32_16x16x64_i8 v[86:89], v[162:165], v[230:233], v[86:89]
	v_mfma_i32_16x16x64_i8 v[82:85], v[170:173], v[230:233], v[82:85]
	v_mfma_i32_16x16x64_i8 v[70:73], v[162:165], v[238:241], v[70:73]
	v_mfma_i32_16x16x64_i8 v[66:69], v[170:173], v[238:241], v[66:69]
	s_barrier
	s_setprio 0
	s_add_i32 s30, s85, s56
	v_lshl_add_u64 v[210:211], s[52:53], 0, v[182:183]
	s_mov_b32 m0, s30
	ds_read_b128 v[178:181], v176 offset:16384
	ds_read_b128 v[198:201], v176 offset:17408
	ds_read_b128 v[202:205], v176 offset:18432
	ds_read_b128 v[206:209], v176 offset:19456
	ds_read_b128 v[226:229], v176 offset:20480
	ds_read_b128 v[230:233], v176 offset:21504
	ds_read_b128 v[234:237], v176 offset:22528
	ds_read_b128 v[238:241], v176 offset:23552
	global_load_lds_dwordx4 v[210:211], off
	s_add_i32 m0, s30, 0x2000
	s_add_u32 s30, s52, 0x80000
	v_lshl_add_u64 v[242:243], s[52:53], 0, v[130:131]
	s_addc_u32 s31, s53, 0
	s_add_i32 s85, vcc_lo, s56
	global_load_lds_dwordx4 v[242:243], off
	v_lshl_add_u64 v[244:245], s[30:31], 0, v[182:183]
	s_mov_b32 m0, s85
	v_lshl_add_u64 v[246:247], s[54:55], 0, v[132:133]
	global_load_lds_dwordx4 v[244:245], off
	v_lshl_add_u64 v[244:245], s[30:31], 0, v[130:131]
	s_add_i32 m0, s85, 0x2000
	s_nop 0
	global_load_lds_dwordx4 v[244:245], off
	v_lshl_add_u64 v[244:245], s[54:55], 0, v[134:135]
	s_mov_b32 m0, s57
	s_nop 0
	global_load_lds_dwordx4 v[244:245], off
	s_mov_b32 m0, s58
	s_nop 0
	global_load_lds_dwordx4 v[246:247], off
	s_waitcnt vmcnt(8)
	s_waitcnt lgkmcnt(0)
	s_setprio 1
	s_barrier
; #define PG8_STAGE(bufoff, gbase, voff) do { _Pragma("unroll") for (int _i = 0; _i < 2; ++_i) \
;         __builtin_amdgcn_global_load_lds((const unsigned*)((const char*)(gbase) + (voff)[_i]), (PG8_LAS unsigned*)(lds + (bufoff) + ldsw + _i * 8192), 16, 0, 0); } while (0)
; #define PG8_LDA(dst, b, h) do { _Pragma("unroll") for (int m = 0; m < 4; ++m) _Pragma("unroll") for (int k = 0; k < 2; ++k) dst[m][k] = *(const PG8_LAS bf16x8*)(lds + PG8_SA(b, h) + aoff + m * 2048 + k * 1024); } while (0)
; #define PG8_LDB(dst, b, h) do { _Pragma("unroll") for (int n = 0; n < 2; ++n) _Pragma("unroll") for (int k = 0; k < 2; ++k) dst[n][k] = *(const PG8_LAS bf16x8*)(lds + PG8_SB(b, h) + boff + n * 2048 + k * 1024); } while (0)
; #define PG8_WAIT_V(n) asm volatile("s_waitcnt vmcnt(" #n ")" ::: "memory")
; #define PG8_WAIT_L(n) asm volatile("s_waitcnt lgkmcnt(" #n ")" ::: "memory")
; #define PG8_BAR __builtin_amdgcn_s_barrier()
; #define PG8_SCHED __builtin_amdgcn_sched_barrier(0)
; template <class Epi, class Sched, bool ALIGN_EPI = false, bool SP2 = false, bool I8 = false, bool F16 = false>
; __device__ __forceinline__ void gemm_phase(PG8_LAS unsigned char* lds, const Gemm g, const Sched& S, const Epi& E) {
;     ...
;             PG8_WAIT_V(8); PG8_WAIT_L(0); PG8_BAR; PG8_MMA(1, 0, At, B0); PG8_MMA(1, 1, At, B1); PG8_BAR; PG8_SCHED;
;             PG8_LDB(B0, 1, 0); PG8_LDB(B1, 1, 1); PG8_SCHED; PG8_LDA(At, 1, 0); PG8_STAGE(PG8_SA(0, 1), a2 + hstep, voffA);
;             PG8_WAIT_V(8); PG8_WAIT_L(0); PG8_BAR; PG8_MMA(0, 0, At, B0); PG8_MMA(0, 1, At, B1); PG8_BAR; PG8_SCHED;
	v_mfma_i32_16x16x64_i8 v[62:65], v[142:145], v[178:181], v[62:65]
	v_mfma_i32_16x16x64_i8 v[58:61], v[150:153], v[178:181], v[58:61]
	v_mfma_i32_16x16x64_i8 v[46:49], v[142:145], v[202:205], v[46:49]
	v_mfma_i32_16x16x64_i8 v[42:45], v[150:153], v[202:205], v[42:45]
	v_mfma_i32_16x16x64_i8 v[30:33], v[142:145], v[226:229], v[30:33]
	v_mfma_i32_16x16x64_i8 v[26:29], v[150:153], v[226:229], v[26:29]
	v_mfma_i32_16x16x64_i8 v[14:17], v[142:145], v[234:237], v[14:17]
	v_mfma_i32_16x16x64_i8 v[10:13], v[150:153], v[234:237], v[10:13]
	v_mfma_i32_16x16x64_i8 v[62:65], v[146:149], v[198:201], v[62:65]
	v_mfma_i32_16x16x64_i8 v[58:61], v[154:157], v[198:201], v[58:61]
	v_mfma_i32_16x16x64_i8 v[46:49], v[146:149], v[206:209], v[46:49]
	v_mfma_i32_16x16x64_i8 v[42:45], v[154:157], v[206:209], v[42:45]
	v_mfma_i32_16x16x64_i8 v[30:33], v[146:149], v[230:233], v[30:33]
	v_mfma_i32_16x16x64_i8 v[26:29], v[154:157], v[230:233], v[26:29]
	v_mfma_i32_16x16x64_i8 v[14:17], v[146:149], v[238:241], v[14:17]
	v_mfma_i32_16x16x64_i8 v[10:13], v[154:157], v[238:241], v[10:13]
	v_mfma_i32_16x16x64_i8 v[54:57], v[158:161], v[178:181], v[54:57]
	v_mfma_i32_16x16x64_i8 v[50:53], v[166:169], v[178:181], v[50:53]
	v_mfma_i32_16x16x64_i8 v[38:41], v[158:161], v[202:205], v[38:41]
	v_mfma_i32_16x16x64_i8 v[34:37], v[166:169], v[202:205], v[34:37]
	v_mfma_i32_16x16x64_i8 v[22:25], v[158:161], v[226:229], v[22:25]
	v_mfma_i32_16x16x64_i8 v[18:21], v[166:169], v[226:229], v[18:21]
	v_mfma_i32_16x16x64_i8 v[6:9], v[158:161], v[234:237], v[6:9]
	v_mfma_i32_16x16x64_i8 v[2:5], v[166:169], v[234:237], v[2:5]
	v_mfma_i32_16x16x64_i8 v[54:57], v[162:165], v[198:201], v[54:57]
	v_mfma_i32_16x16x64_i8 v[50:53], v[170:173], v[198:201], v[50:53]
	v_mfma_i32_16x16x64_i8 v[38:41], v[162:165], v[206:209], v[38:41]
	v_mfma_i32_16x16x64_i8 v[34:37], v[170:173], v[206:209], v[34:37]
	v_mfma_i32_16x16x64_i8 v[22:25], v[162:165], v[230:233], v[22:25]
	v_mfma_i32_16x16x64_i8 v[18:21], v[170:173], v[230:233], v[18:21]
	v_mfma_i32_16x16x64_i8 v[6:9], v[162:165], v[238:241], v[6:9]
	v_mfma_i32_16x16x64_i8 v[2:5], v[170:173], v[238:241], v[2:5]
	s_barrier
	s_setprio 0
	s_add_i32 s85, 0, 0x18000
	s_add_i32 vcc_lo, 0, 0x1c000
	v_add_u32_e32 v154, s85, v174
	v_add_u32_e32 v170, vcc_lo, v174
	ds_read_b128 v[142:145], v154
	ds_read_b128 v[146:149], v154 offset:1024
	ds_read_b128 v[150:153], v154 offset:2048
	ds_read_b128 v[154:157], v154 offset:3072
	ds_read_b128 v[158:161], v170
	ds_read_b128 v[162:165], v170 offset:1024
	ds_read_b128 v[166:169], v170 offset:2048
	ds_read_b128 v[170:173], v170 offset:3072
	s_add_u32 s30, s54, 0x80000
	s_addc_u32 s31, s55, 0
	s_mov_b32 m0, s59
	v_lshl_add_u64 v[248:249], s[30:31], 0, v[134:135]
	ds_read_b128 v[178:181], v176 offset:32768
	ds_read_b128 v[198:201], v176 offset:33792
	ds_read_b128 v[202:205], v176 offset:34816
	ds_read_b128 v[206:209], v176 offset:35840
	ds_read_b128 v[226:229], v176 offset:36864
	ds_read_b128 v[230:233], v176 offset:37888
	ds_read_b128 v[234:237], v176 offset:38912
	ds_read_b128 v[238:241], v176 offset:39936
	global_load_lds_dwordx4 v[248:249], off
	v_lshl_add_u64 v[248:249], s[30:31], 0, v[132:133]
	s_mov_b32 m0, s64
	s_nop 0
	global_load_lds_dwordx4 v[248:249], off
	s_waitcnt vmcnt(8)
	s_waitcnt lgkmcnt(0)
	s_setprio 1
	s_barrier
	v_mfma_i32_16x16x64_i8 v[126:129], v[142:145], v[178:181], v[126:129]
	v_mfma_i32_16x16x64_i8 v[122:125], v[150:153], v[178:181], v[122:125]
	v_mfma_i32_16x16x64_i8 v[110:113], v[142:145], v[202:205], v[110:113]
	v_mfma_i32_16x16x64_i8 v[106:109], v[150:153], v[202:205], v[106:109]
	v_mfma_i32_16x16x64_i8 v[94:97], v[142:145], v[226:229], v[94:97]
	v_mfma_i32_16x16x64_i8 v[90:93], v[150:153], v[226:229], v[90:93]
	v_mfma_i32_16x16x64_i8 v[78:81], v[142:145], v[234:237], v[78:81]
	v_mfma_i32_16x16x64_i8 v[74:77], v[150:153], v[234:237], v[74:77]
	v_mfma_i32_16x16x64_i8 v[126:129], v[146:149], v[198:201], v[126:129]
	v_mfma_i32_16x16x64_i8 v[122:125], v[154:157], v[198:201], v[122:125]
	v_mfma_i32_16x16x64_i8 v[110:113], v[146:149], v[206:209], v[110:113]
	v_mfma_i32_16x16x64_i8 v[106:109], v[154:157], v[206:209], v[106:109]
	v_mfma_i32_16x16x64_i8 v[94:97], v[146:149], v[230:233], v[94:97]
	v_mfma_i32_16x16x64_i8 v[90:93], v[154:157], v[230:233], v[90:93]
	v_mfma_i32_16x16x64_i8 v[78:81], v[146:149], v[238:241], v[78:81]
	v_mfma_i32_16x16x64_i8 v[74:77], v[154:157], v[238:241], v[74:77]
	v_mfma_i32_16x16x64_i8 v[118:121], v[158:161], v[178:181], v[118:121]
	v_mfma_i32_16x16x64_i8 v[114:117], v[166:169], v[178:181], v[114:117]
	v_mfma_i32_16x16x64_i8 v[102:105], v[158:161], v[202:205], v[102:105]
	v_mfma_i32_16x16x64_i8 v[98:101], v[166:169], v[202:205], v[98:101]
	v_mfma_i32_16x16x64_i8 v[86:89], v[158:161], v[226:229], v[86:89]
	v_mfma_i32_16x16x64_i8 v[82:85], v[166:169], v[226:229], v[82:85]
	v_mfma_i32_16x16x64_i8 v[70:73], v[158:161], v[234:237], v[70:73]
	v_mfma_i32_16x16x64_i8 v[66:69], v[166:169], v[234:237], v[66:69]
	v_mfma_i32_16x16x64_i8 v[118:121], v[162:165], v[198:201], v[118:121]
	v_mfma_i32_16x16x64_i8 v[114:117], v[170:173], v[198:201], v[114:117]
	v_mfma_i32_16x16x64_i8 v[102:105], v[162:165], v[206:209], v[102:105]
	v_mfma_i32_16x16x64_i8 v[98:101], v[170:173], v[206:209], v[98:101]
	v_mfma_i32_16x16x64_i8 v[86:89], v[162:165], v[230:233], v[86:89]
	v_mfma_i32_16x16x64_i8 v[82:85], v[170:173], v[230:233], v[82:85]
	v_mfma_i32_16x16x64_i8 v[70:73], v[162:165], v[238:241], v[70:73]
	v_mfma_i32_16x16x64_i8 v[66:69], v[170:173], v[238:241], v[66:69]
	s_barrier
; #define PG8_STAGE(bufoff, gbase, voff) do { _Pragma("unroll") for (int _i = 0; _i < 2; ++_i) \
;         __builtin_amdgcn_global_load_lds((const unsigned*)((const char*)(gbase) + (voff)[_i]), (PG8_LAS unsigned*)(lds + (bufoff) + ldsw + _i * 8192), 16, 0, 0); } while (0)
; #define PG8_LDA(dst, b, h) do { _Pragma("unroll") for (int m = 0; m < 4; ++m) _Pragma("unroll") for (int k = 0; k < 2; ++k) dst[m][k] = *(const PG8_LAS bf16x8*)(lds + PG8_SA(b, h) + aoff + m * 2048 + k * 1024); } while (0)
; #define PG8_WAIT_V(n) asm volatile("s_waitcnt vmcnt(" #n ")" ::: "memory")
; #define PG8_WAIT_L(n) asm volatile("s_waitcnt lgkmcnt(" #n ")" ::: "memory")
; #define PG8_BAR __builtin_amdgcn_s_barrier()
; #define PG8_SCHED __builtin_amdgcn_sched_barrier(0)
; template <class Epi, class Sched, bool ALIGN_EPI = false, bool SP2 = false, bool I8 = false, bool F16 = false>
; __device__ __forceinline__ void gemm_phase(PG8_LAS unsigned char* lds, const Gemm g, const Sched& S, const Epi& E) {
;     ...
;             PG8_LDA(At, 1, 1); PG8_STAGE(PG8_SB(1, 0), b3, voffB); PG8_STAGE(PG8_SB(1, 1), b3 + hstep, voffB); PG8_STAGE(PG8_SA(1, 0), a3, voffA);
;             PG8_WAIT_V(8); PG8_WAIT_L(0); PG8_BAR; PG8_MMA(1, 0, At, B0); PG8_MMA(1, 1, At, B1); PG8_BAR; PG8_SCHED;
;     ...
;         if constexpr (ALIGN_EPI) { if (wr == 0) PG8_BAR; }
	s_setprio 0
	s_add_i32 s30, s85, s56
	v_lshl_add_u64 v[210:211], v[210:211], 0, s[74:75]
	s_mov_b32 m0, s30
	ds_read_b128 v[178:181], v176 offset:49152
	ds_read_b128 v[198:201], v176 offset:50176
	ds_read_b128 v[202:205], v176 offset:51200
	ds_read_b128 v[206:209], v176 offset:52224
	ds_read_b128 v[226:229], v176 offset:53248
	ds_read_b128 v[230:233], v176 offset:54272
	ds_read_b128 v[234:237], v176 offset:55296
	ds_read_b128 v[238:241], v176 offset:56320
	global_load_lds_dwordx4 v[210:211], off
	s_add_i32 m0, s30, 0x2000
	s_add_u32 s30, s52, 0x80080
	v_lshl_add_u64 v[210:211], v[242:243], 0, s[74:75]
	s_addc_u32 s31, s53, 0
	s_add_i32 s52, vcc_lo, s56
	global_load_lds_dwordx4 v[210:211], off
	v_lshl_add_u64 v[210:211], s[30:31], 0, v[182:183]
	s_mov_b32 m0, s52
	s_nop 0
	global_load_lds_dwordx4 v[210:211], off
	v_lshl_add_u64 v[210:211], s[30:31], 0, v[130:131]
	s_add_i32 m0, s52, 0x2000
	s_nop 0
	global_load_lds_dwordx4 v[210:211], off
	v_lshl_add_u64 v[210:211], v[244:245], 0, s[74:75]
	s_mov_b32 m0, s62
	s_nop 0
	global_load_lds_dwordx4 v[210:211], off
	v_lshl_add_u64 v[210:211], v[246:247], 0, s[74:75]
	s_mov_b32 m0, s65
	s_nop 0
	global_load_lds_dwordx4 v[210:211], off
	s_waitcnt vmcnt(8)
	s_waitcnt lgkmcnt(0)
	s_setprio 1
	s_barrier
	v_mfma_i32_16x16x64_i8 v[62:65], v[142:145], v[178:181], v[62:65]
	v_mfma_i32_16x16x64_i8 v[58:61], v[150:153], v[178:181], v[58:61]
	v_mfma_i32_16x16x64_i8 v[46:49], v[142:145], v[202:205], v[46:49]
	v_mfma_i32_16x16x64_i8 v[42:45], v[150:153], v[202:205], v[42:45]
	v_mfma_i32_16x16x64_i8 v[30:33], v[142:145], v[226:229], v[30:33]
	v_mfma_i32_16x16x64_i8 v[26:29], v[150:153], v[226:229], v[26:29]
	v_mfma_i32_16x16x64_i8 v[14:17], v[142:145], v[234:237], v[14:17]
	v_mfma_i32_16x16x64_i8 v[10:13], v[150:153], v[234:237], v[10:13]
	v_mfma_i32_16x16x64_i8 v[62:65], v[146:149], v[198:201], v[62:65]
	v_mfma_i32_16x16x64_i8 v[58:61], v[154:157], v[198:201], v[58:61]
	v_mfma_i32_16x16x64_i8 v[46:49], v[146:149], v[206:209], v[46:49]
	v_mfma_i32_16x16x64_i8 v[42:45], v[154:157], v[206:209], v[42:45]
	v_mfma_i32_16x16x64_i8 v[30:33], v[146:149], v[230:233], v[30:33]
	v_mfma_i32_16x16x64_i8 v[26:29], v[154:157], v[230:233], v[26:29]
	v_mfma_i32_16x16x64_i8 v[14:17], v[146:149], v[238:241], v[14:17]
	v_mfma_i32_16x16x64_i8 v[10:13], v[154:157], v[238:241], v[10:13]
	v_mfma_i32_16x16x64_i8 v[54:57], v[158:161], v[178:181], v[54:57]
	v_mfma_i32_16x16x64_i8 v[50:53], v[166:169], v[178:181], v[50:53]
	v_mfma_i32_16x16x64_i8 v[38:41], v[158:161], v[202:205], v[38:41]
	v_mfma_i32_16x16x64_i8 v[34:37], v[166:169], v[202:205], v[34:37]
	v_mfma_i32_16x16x64_i8 v[22:25], v[158:161], v[226:229], v[22:25]
	v_mfma_i32_16x16x64_i8 v[18:21], v[166:169], v[226:229], v[18:21]
	v_mfma_i32_16x16x64_i8 v[6:9], v[158:161], v[234:237], v[6:9]
	v_mfma_i32_16x16x64_i8 v[2:5], v[166:169], v[234:237], v[2:5]
	v_mfma_i32_16x16x64_i8 v[54:57], v[162:165], v[198:201], v[54:57]
	v_mfma_i32_16x16x64_i8 v[50:53], v[170:173], v[198:201], v[50:53]
	v_mfma_i32_16x16x64_i8 v[38:41], v[162:165], v[206:209], v[38:41]
	v_mfma_i32_16x16x64_i8 v[34:37], v[170:173], v[206:209], v[34:37]
	v_mfma_i32_16x16x64_i8 v[22:25], v[162:165], v[230:233], v[22:25]
	v_mfma_i32_16x16x64_i8 v[18:21], v[170:173], v[230:233], v[18:21]
	v_mfma_i32_16x16x64_i8 v[6:9], v[162:165], v[238:241], v[6:9]
	v_mfma_i32_16x16x64_i8 v[2:5], v[170:173], v[238:241], v[2:5]
	s_barrier
	s_setprio 0
	s_add_i32 s83, s83, 2
	s_add_u32 s6, s6, 0x100
	s_addc_u32 s7, s7, 0
	s_add_u32 s79, s79, 0x100
	s_addc_u32 s81, s81, 0
	s_cmp_gt_u32 s83, 29
	s_cbranch_scc0 .LBB0_332
	s_and_b64 vcc, exec, s[36:37]
	s_cbranch_vccz .LBB0_335
	s_barrier

; #define PG8_STAGE(bufoff, gbase, voff) do { _Pragma("unroll") for (int _i = 0; _i < 2; ++_i) \
;         __builtin_amdgcn_global_load_lds((const unsigned*)((const char*)(gbase) + (voff)[_i]), (PG8_LAS unsigned*)(lds + (bufoff) + ldsw + _i * 8192), 16, 0, 0); } while (0)
; #define PG8_LDA(dst, b, h) do { _Pragma("unroll") for (int m = 0; m < 4; ++m) _Pragma("unroll") for (int k = 0; k < 2; ++k) dst[m][k] = *(const PG8_LAS bf16x8*)(lds + PG8_SA(b, h) + aoff + m * 2048 + k * 1024); } while (0)
; #define PG8_LDB(dst, b, h) do { _Pragma("unroll") for (int n = 0; n < 2; ++n) _Pragma("unroll") for (int k = 0; k < 2; ++k) dst[n][k] = *(const PG8_LAS bf16x8*)(lds + PG8_SB(b, h) + boff + n * 2048 + k * 1024); } while (0)
; #define PG8_WAIT_V(n) asm volatile("s_waitcnt vmcnt(" #n ")" ::: "memory")
; #define PG8_WAIT_L(n) asm volatile("s_waitcnt lgkmcnt(" #n ")" ::: "memory")
; #define PG8_BAR __builtin_amdgcn_s_barrier()
; #define PG8_SCHED __builtin_amdgcn_sched_barrier(0)
; template <class Epi, class Sched, bool ALIGN_EPI = false, bool SP2 = false, bool I8 = false, bool F16 = false>
; __device__ __forceinline__ void gemm_phase(PG8_LAS unsigned char* lds, const Gemm g, const Sched& S, const Epi& E) {
;     ...
;         for (int t = 0; t < nt; t += 2) {
;             const bool last = (t == nt - 2);
;             const char* a1 = cA + (size_t)(t + 1) * kstep;
;             const char* a2 = last ? nA : cA + (size_t)(t + 2) * kstep; const char* b2 = last ? nB : cB + (size_t)(t + 2) * kstep;
;             const char* a3 = a2 + kstep; const char* b3 = b2 + kstep;
;             if (last && has_next) S.a_ready(nxt);
;             if constexpr (SP2) {
;             PG8_LDB(B0, 0, 0); PG8_LDB(B1, 0, 1); PG8_SCHED; PG8_LDA(At, 0, 0); PG8_STAGE(PG8_SA(1, 1), a1 + hstep, voffA);
;             PG8_WAIT_V(8); PG8_WAIT_L(0); PG8_BAR; PG8_MMA(0, 0, At, B0); PG8_MMA(0, 1, At, B1); PG8_BAR; PG8_SCHED;
;             PG8_LDA(At, 0, 1); PG8_STAGE(PG8_SB(0, 0), b2, voffB); PG8_STAGE(PG8_SB(0, 1), b2 + hstep, voffB); PG8_STAGE(PG8_SA(0, 0), a2, voffA);
;             PG8_WAIT_V(8); PG8_WAIT_L(0); PG8_BAR; PG8_MMA(1, 0, At, B0); PG8_MMA(1, 1, At, B1); PG8_BAR; PG8_SCHED;
.LBB0_916:
	s_add_u32 s30, s50, 0xfff00080
	s_addc_u32 s31, s51, -1
	s_add_i32 s85, 0, 0x10000
	s_cmp_eq_u32 s83, 60
	s_cselect_b32 s55, s43, s31
	s_cselect_b32 s54, s70, s30
	s_cselect_b32 s53, s37, s81
	s_cselect_b32 s52, s71, s79
	s_add_i32 vcc_lo, 0, 0x14000
	v_add_u32_e32 v142, s85, v176
	v_add_u32_e32 v168, vcc_lo, v176
	ds_read_b128 v[130:133], v142
	ds_read_b128 v[134:137], v142 offset:1024
	ds_read_b128 v[138:141], v142 offset:2048
	ds_read_b128 v[142:145], v142 offset:3072
	ds_read_b128 v[146:149], v168
	ds_read_b128 v[150:153], v168 offset:1024
	ds_read_b128 v[164:167], v168 offset:2048
	ds_read_b128 v[168:171], v168 offset:3072
	v_lshl_add_u64 v[180:181], s[50:51], 0, v[160:161]
	s_add_i32 m0, s57, 0xc000
	ds_read_b128 v[172:175], v178
	ds_read_b128 v[198:201], v178 offset:1024
	ds_read_b128 v[202:205], v178 offset:2048
	ds_read_b128 v[206:209], v178 offset:3072
	ds_read_b128 v[226:229], v178 offset:4096
	ds_read_b128 v[230:233], v178 offset:5120
	ds_read_b128 v[234:237], v178 offset:6144
	ds_read_b128 v[238:241], v178 offset:7168
	global_load_lds_dwordx4 v[180:181], off
	v_lshl_add_u64 v[180:181], s[50:51], 0, v[162:163]
	s_add_i32 m0, s57, 0xe000
	s_nop 0
	global_load_lds_dwordx4 v[180:181], off
	s_waitcnt vmcnt(8)
	s_waitcnt lgkmcnt(0)
	s_setprio 1
	s_barrier
	v_mfma_f32_16x16x32_bf16 v[126:129], v[130:133], v[172:175], v[126:129]
	v_mfma_f32_16x16x32_bf16 v[122:125], v[138:141], v[172:175], v[122:125]
	v_mfma_f32_16x16x32_bf16 v[110:113], v[130:133], v[202:205], v[110:113]
	v_mfma_f32_16x16x32_bf16 v[106:109], v[138:141], v[202:205], v[106:109]
	v_mfma_f32_16x16x32_bf16 v[98:101], v[130:133], v[226:229], v[98:101]
	v_mfma_f32_16x16x32_bf16 v[90:93], v[138:141], v[226:229], v[90:93]
	v_mfma_f32_16x16x32_bf16 v[82:85], v[130:133], v[234:237], v[82:85]
	v_mfma_f32_16x16x32_bf16 v[74:77], v[138:141], v[234:237], v[74:77]
	v_mfma_f32_16x16x32_bf16 v[126:129], v[134:137], v[198:201], v[126:129]
	v_mfma_f32_16x16x32_bf16 v[122:125], v[142:145], v[198:201], v[122:125]
	v_mfma_f32_16x16x32_bf16 v[110:113], v[134:137], v[206:209], v[110:113]
	v_mfma_f32_16x16x32_bf16 v[106:109], v[142:145], v[206:209], v[106:109]
	v_mfma_f32_16x16x32_bf16 v[98:101], v[134:137], v[230:233], v[98:101]
	v_mfma_f32_16x16x32_bf16 v[90:93], v[142:145], v[230:233], v[90:93]
	v_mfma_f32_16x16x32_bf16 v[82:85], v[134:137], v[238:241], v[82:85]
	v_mfma_f32_16x16x32_bf16 v[74:77], v[142:145], v[238:241], v[74:77]
	v_mfma_f32_16x16x32_bf16 v[118:121], v[146:149], v[172:175], v[118:121]
	v_mfma_f32_16x16x32_bf16 v[114:117], v[164:167], v[172:175], v[114:117]
	v_mfma_f32_16x16x32_bf16 v[102:105], v[146:149], v[202:205], v[102:105]
	v_mfma_f32_16x16x32_bf16 v[94:97], v[164:167], v[202:205], v[94:97]
	v_mfma_f32_16x16x32_bf16 v[86:89], v[146:149], v[226:229], v[86:89]
	v_mfma_f32_16x16x32_bf16 v[78:81], v[164:167], v[226:229], v[78:81]
	v_mfma_f32_16x16x32_bf16 v[70:73], v[146:149], v[234:237], v[70:73]
	v_mfma_f32_16x16x32_bf16 v[66:69], v[164:167], v[234:237], v[66:69]
	v_mfma_f32_16x16x32_bf16 v[118:121], v[150:153], v[198:201], v[118:121]
	v_mfma_f32_16x16x32_bf16 v[114:117], v[168:171], v[198:201], v[114:117]
	v_mfma_f32_16x16x32_bf16 v[102:105], v[150:153], v[206:209], v[102:105]
	v_mfma_f32_16x16x32_bf16 v[94:97], v[168:171], v[206:209], v[94:97]
	v_mfma_f32_16x16x32_bf16 v[86:89], v[150:153], v[230:233], v[86:89]
	v_mfma_f32_16x16x32_bf16 v[78:81], v[168:171], v[230:233], v[78:81]
	v_mfma_f32_16x16x32_bf16 v[70:73], v[150:153], v[238:241], v[70:73]
	v_mfma_f32_16x16x32_bf16 v[66:69], v[168:171], v[238:241], v[66:69]
	s_barrier
	s_setprio 0
	s_add_i32 s30, s85, s56
	v_lshl_add_u64 v[180:181], s[52:53], 0, v[182:183]
	s_mov_b32 m0, s30
	ds_read_b128 v[172:175], v178 offset:16384
	ds_read_b128 v[198:201], v178 offset:17408
	ds_read_b128 v[202:205], v178 offset:18432
	ds_read_b128 v[206:209], v178 offset:19456
	ds_read_b128 v[226:229], v178 offset:20480
	ds_read_b128 v[230:233], v178 offset:21504
	ds_read_b128 v[234:237], v178 offset:22528
	ds_read_b128 v[238:241], v178 offset:23552
	global_load_lds_dwordx4 v[180:181], off
	s_add_i32 m0, s30, 0x2000
	s_add_u32 s30, s52, 0x100000
	v_lshl_add_u64 v[210:211], s[52:53], 0, v[154:155]
	s_addc_u32 s31, s53, 0
	s_add_i32 s85, vcc_lo, s56
	global_load_lds_dwordx4 v[210:211], off
	v_lshl_add_u64 v[242:243], s[30:31], 0, v[182:183]
	s_mov_b32 m0, s85
	v_lshl_add_u64 v[244:245], s[54:55], 0, v[156:157]
	global_load_lds_dwordx4 v[242:243], off
	v_lshl_add_u64 v[242:243], s[30:31], 0, v[154:155]
	s_add_i32 m0, s85, 0x2000
	s_nop 0
	global_load_lds_dwordx4 v[242:243], off
	v_lshl_add_u64 v[242:243], s[54:55], 0, v[158:159]
	s_mov_b32 m0, s57
	s_nop 0
	global_load_lds_dwordx4 v[242:243], off
	s_mov_b32 m0, s58
	s_nop 0
	global_load_lds_dwordx4 v[244:245], off
	s_waitcnt vmcnt(8)
	s_waitcnt lgkmcnt(0)
	s_setprio 1
	s_barrier
; #define PG8_STAGE(bufoff, gbase, voff) do { _Pragma("unroll") for (int _i = 0; _i < 2; ++_i) \
;         __builtin_amdgcn_global_load_lds((const unsigned*)((const char*)(gbase) + (voff)[_i]), (PG8_LAS unsigned*)(lds + (bufoff) + ldsw + _i * 8192), 16, 0, 0); } while (0)
; #define PG8_LDA(dst, b, h) do { _Pragma("unroll") for (int m = 0; m < 4; ++m) _Pragma("unroll") for (int k = 0; k < 2; ++k) dst[m][k] = *(const PG8_LAS bf16x8*)(lds + PG8_SA(b, h) + aoff + m * 2048 + k * 1024); } while (0)
; #define PG8_LDB(dst, b, h) do { _Pragma("unroll") for (int n = 0; n < 2; ++n) _Pragma("unroll") for (int k = 0; k < 2; ++k) dst[n][k] = *(const PG8_LAS bf16x8*)(lds + PG8_SB(b, h) + boff + n * 2048 + k * 1024); } while (0)
; #define PG8_WAIT_V(n) asm volatile("s_waitcnt vmcnt(" #n ")" ::: "memory")
; #define PG8_WAIT_L(n) asm volatile("s_waitcnt lgkmcnt(" #n ")" ::: "memory")
; #define PG8_BAR __builtin_amdgcn_s_barrier()
; #define PG8_SCHED __builtin_amdgcn_sched_barrier(0)
; template <class Epi, class Sched, bool ALIGN_EPI = false, bool SP2 = false, bool I8 = false, bool F16 = false>
; __device__ __forceinline__ void gemm_phase(PG8_LAS unsigned char* lds, const Gemm g, const Sched& S, const Epi& E) {
;     ...
;             PG8_WAIT_V(8); PG8_WAIT_L(0); PG8_BAR; PG8_MMA(1, 0, At, B0); PG8_MMA(1, 1, At, B1); PG8_BAR; PG8_SCHED;
;             PG8_LDB(B0, 1, 0); PG8_LDB(B1, 1, 1); PG8_SCHED; PG8_LDA(At, 1, 0); PG8_STAGE(PG8_SA(0, 1), a2 + hstep, voffA);
;             PG8_WAIT_V(8); PG8_WAIT_L(0); PG8_BAR; PG8_MMA(0, 0, At, B0); PG8_MMA(0, 1, At, B1); PG8_BAR; PG8_SCHED;
	v_mfma_f32_16x16x32_bf16 v[62:65], v[130:133], v[172:175], v[62:65]
	v_mfma_f32_16x16x32_bf16 v[58:61], v[138:141], v[172:175], v[58:61]
	v_mfma_f32_16x16x32_bf16 v[50:53], v[130:133], v[202:205], v[50:53]
	v_mfma_f32_16x16x32_bf16 v[42:45], v[138:141], v[202:205], v[42:45]
	v_mfma_f32_16x16x32_bf16 v[34:37], v[130:133], v[226:229], v[34:37]
	v_mfma_f32_16x16x32_bf16 v[26:29], v[138:141], v[226:229], v[26:29]
	v_mfma_f32_16x16x32_bf16 v[18:21], v[130:133], v[234:237], v[18:21]
	v_mfma_f32_16x16x32_bf16 v[10:13], v[138:141], v[234:237], v[10:13]
	v_mfma_f32_16x16x32_bf16 v[62:65], v[134:137], v[198:201], v[62:65]
	v_mfma_f32_16x16x32_bf16 v[58:61], v[142:145], v[198:201], v[58:61]
	v_mfma_f32_16x16x32_bf16 v[50:53], v[134:137], v[206:209], v[50:53]
	v_mfma_f32_16x16x32_bf16 v[42:45], v[142:145], v[206:209], v[42:45]
	v_mfma_f32_16x16x32_bf16 v[34:37], v[134:137], v[230:233], v[34:37]
	v_mfma_f32_16x16x32_bf16 v[26:29], v[142:145], v[230:233], v[26:29]
	v_mfma_f32_16x16x32_bf16 v[18:21], v[134:137], v[238:241], v[18:21]
	v_mfma_f32_16x16x32_bf16 v[10:13], v[142:145], v[238:241], v[10:13]
	v_mfma_f32_16x16x32_bf16 v[54:57], v[146:149], v[172:175], v[54:57]
	v_mfma_f32_16x16x32_bf16 v[46:49], v[164:167], v[172:175], v[46:49]
	v_mfma_f32_16x16x32_bf16 v[38:41], v[146:149], v[202:205], v[38:41]
	v_mfma_f32_16x16x32_bf16 v[30:33], v[164:167], v[202:205], v[30:33]
	v_mfma_f32_16x16x32_bf16 v[22:25], v[146:149], v[226:229], v[22:25]
	v_mfma_f32_16x16x32_bf16 v[14:17], v[164:167], v[226:229], v[14:17]
	v_mfma_f32_16x16x32_bf16 v[6:9], v[146:149], v[234:237], v[6:9]
	v_mfma_f32_16x16x32_bf16 v[2:5], v[164:167], v[234:237], v[2:5]
	v_mfma_f32_16x16x32_bf16 v[54:57], v[150:153], v[198:201], v[54:57]
	v_mfma_f32_16x16x32_bf16 v[46:49], v[168:171], v[198:201], v[46:49]
	v_mfma_f32_16x16x32_bf16 v[38:41], v[150:153], v[206:209], v[38:41]
	v_mfma_f32_16x16x32_bf16 v[30:33], v[168:171], v[206:209], v[30:33]
	v_mfma_f32_16x16x32_bf16 v[22:25], v[150:153], v[230:233], v[22:25]
	v_mfma_f32_16x16x32_bf16 v[14:17], v[168:171], v[230:233], v[14:17]
	v_mfma_f32_16x16x32_bf16 v[6:9], v[150:153], v[238:241], v[6:9]
	v_mfma_f32_16x16x32_bf16 v[2:5], v[168:171], v[238:241], v[2:5]
	s_barrier
	s_setprio 0
	s_add_i32 s85, 0, 0x18000
	s_add_i32 vcc_lo, 0, 0x1c000
	v_add_u32_e32 v142, s85, v176
	v_add_u32_e32 v168, vcc_lo, v176
	ds_read_b128 v[130:133], v142
	ds_read_b128 v[134:137], v142 offset:1024
	ds_read_b128 v[138:141], v142 offset:2048
	ds_read_b128 v[142:145], v142 offset:3072
	ds_read_b128 v[146:149], v168
	ds_read_b128 v[150:153], v168 offset:1024
	ds_read_b128 v[164:167], v168 offset:2048
	ds_read_b128 v[168:171], v168 offset:3072
	s_add_u32 s30, s54, 0x100000
	s_addc_u32 s31, s55, 0
	s_mov_b32 m0, s59
	v_lshl_add_u64 v[246:247], s[30:31], 0, v[158:159]
	ds_read_b128 v[172:175], v178 offset:32768
	ds_read_b128 v[198:201], v178 offset:33792
	ds_read_b128 v[202:205], v178 offset:34816
	ds_read_b128 v[206:209], v178 offset:35840
	ds_read_b128 v[226:229], v178 offset:36864
	ds_read_b128 v[230:233], v178 offset:37888
	ds_read_b128 v[234:237], v178 offset:38912
	ds_read_b128 v[238:241], v178 offset:39936
	global_load_lds_dwordx4 v[246:247], off
	v_lshl_add_u64 v[246:247], s[30:31], 0, v[156:157]
	s_mov_b32 m0, s62
	s_nop 0
	global_load_lds_dwordx4 v[246:247], off
	s_waitcnt vmcnt(8)
	s_waitcnt lgkmcnt(0)
	s_setprio 1
	s_barrier
	v_mfma_f32_16x16x32_bf16 v[126:129], v[130:133], v[172:175], v[126:129]
	v_mfma_f32_16x16x32_bf16 v[122:125], v[138:141], v[172:175], v[122:125]
	v_mfma_f32_16x16x32_bf16 v[110:113], v[130:133], v[202:205], v[110:113]
	v_mfma_f32_16x16x32_bf16 v[106:109], v[138:141], v[202:205], v[106:109]
	v_mfma_f32_16x16x32_bf16 v[98:101], v[130:133], v[226:229], v[98:101]
	v_mfma_f32_16x16x32_bf16 v[90:93], v[138:141], v[226:229], v[90:93]
	v_mfma_f32_16x16x32_bf16 v[82:85], v[130:133], v[234:237], v[82:85]
	v_mfma_f32_16x16x32_bf16 v[74:77], v[138:141], v[234:237], v[74:77]
	v_mfma_f32_16x16x32_bf16 v[126:129], v[134:137], v[198:201], v[126:129]
	v_mfma_f32_16x16x32_bf16 v[122:125], v[142:145], v[198:201], v[122:125]
	v_mfma_f32_16x16x32_bf16 v[110:113], v[134:137], v[206:209], v[110:113]
	v_mfma_f32_16x16x32_bf16 v[106:109], v[142:145], v[206:209], v[106:109]
	v_mfma_f32_16x16x32_bf16 v[98:101], v[134:137], v[230:233], v[98:101]
	v_mfma_f32_16x16x32_bf16 v[90:93], v[142:145], v[230:233], v[90:93]
	v_mfma_f32_16x16x32_bf16 v[82:85], v[134:137], v[238:241], v[82:85]
	v_mfma_f32_16x16x32_bf16 v[74:77], v[142:145], v[238:241], v[74:77]
	v_mfma_f32_16x16x32_bf16 v[118:121], v[146:149], v[172:175], v[118:121]
	v_mfma_f32_16x16x32_bf16 v[114:117], v[164:167], v[172:175], v[114:117]
	v_mfma_f32_16x16x32_bf16 v[102:105], v[146:149], v[202:205], v[102:105]
	v_mfma_f32_16x16x32_bf16 v[94:97], v[164:167], v[202:205], v[94:97]
	v_mfma_f32_16x16x32_bf16 v[86:89], v[146:149], v[226:229], v[86:89]
	v_mfma_f32_16x16x32_bf16 v[78:81], v[164:167], v[226:229], v[78:81]
	v_mfma_f32_16x16x32_bf16 v[70:73], v[146:149], v[234:237], v[70:73]
	v_mfma_f32_16x16x32_bf16 v[66:69], v[164:167], v[234:237], v[66:69]
	v_mfma_f32_16x16x32_bf16 v[118:121], v[150:153], v[198:201], v[118:121]
	v_mfma_f32_16x16x32_bf16 v[114:117], v[168:171], v[198:201], v[114:117]
	v_mfma_f32_16x16x32_bf16 v[102:105], v[150:153], v[206:209], v[102:105]
	v_mfma_f32_16x16x32_bf16 v[94:97], v[168:171], v[206:209], v[94:97]
	v_mfma_f32_16x16x32_bf16 v[86:89], v[150:153], v[230:233], v[86:89]
	v_mfma_f32_16x16x32_bf16 v[78:81], v[168:171], v[230:233], v[78:81]
	v_mfma_f32_16x16x32_bf16 v[70:73], v[150:153], v[238:241], v[70:73]
	v_mfma_f32_16x16x32_bf16 v[66:69], v[168:171], v[238:241], v[66:69]
	s_barrier
; #define PG8_STAGE(bufoff, gbase, voff) do { _Pragma("unroll") for (int _i = 0; _i < 2; ++_i) \
;         __builtin_amdgcn_global_load_lds((const unsigned*)((const char*)(gbase) + (voff)[_i]), (PG8_LAS unsigned*)(lds + (bufoff) + ldsw + _i * 8192), 16, 0, 0); } while (0)
; #define PG8_LDA(dst, b, h) do { _Pragma("unroll") for (int m = 0; m < 4; ++m) _Pragma("unroll") for (int k = 0; k < 2; ++k) dst[m][k] = *(const PG8_LAS bf16x8*)(lds + PG8_SA(b, h) + aoff + m * 2048 + k * 1024); } while (0)
; #define PG8_WAIT_V(n) asm volatile("s_waitcnt vmcnt(" #n ")" ::: "memory")
; #define PG8_WAIT_L(n) asm volatile("s_waitcnt lgkmcnt(" #n ")" ::: "memory")
; #define PG8_BAR __builtin_amdgcn_s_barrier()
; #define PG8_SCHED __builtin_amdgcn_sched_barrier(0)
; template <class Epi, class Sched, bool ALIGN_EPI = false, bool SP2 = false, bool I8 = false, bool F16 = false>
; __device__ __forceinline__ void gemm_phase(PG8_LAS unsigned char* lds, const Gemm g, const Sched& S, const Epi& E) {
;     ...
;             PG8_LDA(At, 1, 1); PG8_STAGE(PG8_SB(1, 0), b3, voffB); PG8_STAGE(PG8_SB(1, 1), b3 + hstep, voffB); PG8_STAGE(PG8_SA(1, 0), a3, voffA);
;             PG8_WAIT_V(8); PG8_WAIT_L(0); PG8_BAR; PG8_MMA(1, 0, At, B0); PG8_MMA(1, 1, At, B1); PG8_BAR; PG8_SCHED;
;     ...
;         if constexpr (ALIGN_EPI) { if (wr == 0) PG8_BAR; }
	s_setprio 0
	s_add_i32 s30, s85, s56
	v_lshl_add_u64 v[180:181], v[180:181], 0, s[74:75]
	s_mov_b32 m0, s30
	ds_read_b128 v[172:175], v178 offset:49152
	ds_read_b128 v[198:201], v178 offset:50176
	ds_read_b128 v[202:205], v178 offset:51200
	ds_read_b128 v[206:209], v178 offset:52224
	ds_read_b128 v[226:229], v178 offset:53248
	ds_read_b128 v[230:233], v178 offset:54272
	ds_read_b128 v[234:237], v178 offset:55296
	ds_read_b128 v[238:241], v178 offset:56320
	global_load_lds_dwordx4 v[180:181], off
	s_add_i32 m0, s30, 0x2000
	s_add_u32 s30, s52, 0x100080
	v_lshl_add_u64 v[180:181], v[210:211], 0, s[74:75]
	s_addc_u32 s31, s53, 0
	s_add_i32 s52, vcc_lo, s56
	global_load_lds_dwordx4 v[180:181], off
	v_lshl_add_u64 v[180:181], s[30:31], 0, v[182:183]
	s_mov_b32 m0, s52
	s_nop 0
	global_load_lds_dwordx4 v[180:181], off
	v_lshl_add_u64 v[180:181], s[30:31], 0, v[154:155]
	s_add_i32 m0, s52, 0x2000
	s_nop 0
	global_load_lds_dwordx4 v[180:181], off
	v_lshl_add_u64 v[180:181], v[242:243], 0, s[74:75]
	s_mov_b32 m0, s64
	s_nop 0
	global_load_lds_dwordx4 v[180:181], off
	v_lshl_add_u64 v[180:181], v[244:245], 0, s[74:75]
	s_mov_b32 m0, s65
	s_nop 0
	global_load_lds_dwordx4 v[180:181], off
	s_waitcnt vmcnt(8)
	s_waitcnt lgkmcnt(0)
	s_setprio 1
	s_barrier
	v_mfma_f32_16x16x32_bf16 v[62:65], v[130:133], v[172:175], v[62:65]
	v_mfma_f32_16x16x32_bf16 v[58:61], v[138:141], v[172:175], v[58:61]
	v_mfma_f32_16x16x32_bf16 v[50:53], v[130:133], v[202:205], v[50:53]
	v_mfma_f32_16x16x32_bf16 v[42:45], v[138:141], v[202:205], v[42:45]
	v_mfma_f32_16x16x32_bf16 v[34:37], v[130:133], v[226:229], v[34:37]
	v_mfma_f32_16x16x32_bf16 v[26:29], v[138:141], v[226:229], v[26:29]
	v_mfma_f32_16x16x32_bf16 v[18:21], v[130:133], v[234:237], v[18:21]
	v_mfma_f32_16x16x32_bf16 v[10:13], v[138:141], v[234:237], v[10:13]
	v_mfma_f32_16x16x32_bf16 v[62:65], v[134:137], v[198:201], v[62:65]
	v_mfma_f32_16x16x32_bf16 v[58:61], v[142:145], v[198:201], v[58:61]
	v_mfma_f32_16x16x32_bf16 v[50:53], v[134:137], v[206:209], v[50:53]
	v_mfma_f32_16x16x32_bf16 v[42:45], v[142:145], v[206:209], v[42:45]
	v_mfma_f32_16x16x32_bf16 v[34:37], v[134:137], v[230:233], v[34:37]
	v_mfma_f32_16x16x32_bf16 v[26:29], v[142:145], v[230:233], v[26:29]
	v_mfma_f32_16x16x32_bf16 v[18:21], v[134:137], v[238:241], v[18:21]
	v_mfma_f32_16x16x32_bf16 v[10:13], v[142:145], v[238:241], v[10:13]
	v_mfma_f32_16x16x32_bf16 v[54:57], v[146:149], v[172:175], v[54:57]
	v_mfma_f32_16x16x32_bf16 v[46:49], v[164:167], v[172:175], v[46:49]
	v_mfma_f32_16x16x32_bf16 v[38:41], v[146:149], v[202:205], v[38:41]
	v_mfma_f32_16x16x32_bf16 v[30:33], v[164:167], v[202:205], v[30:33]
	v_mfma_f32_16x16x32_bf16 v[22:25], v[146:149], v[226:229], v[22:25]
	v_mfma_f32_16x16x32_bf16 v[14:17], v[164:167], v[226:229], v[14:17]
	v_mfma_f32_16x16x32_bf16 v[6:9], v[146:149], v[234:237], v[6:9]
	v_mfma_f32_16x16x32_bf16 v[2:5], v[164:167], v[234:237], v[2:5]
	v_mfma_f32_16x16x32_bf16 v[54:57], v[150:153], v[198:201], v[54:57]
	v_mfma_f32_16x16x32_bf16 v[46:49], v[168:171], v[198:201], v[46:49]
	v_mfma_f32_16x16x32_bf16 v[38:41], v[150:153], v[206:209], v[38:41]
	v_mfma_f32_16x16x32_bf16 v[30:33], v[168:171], v[206:209], v[30:33]
	v_mfma_f32_16x16x32_bf16 v[22:25], v[150:153], v[230:233], v[22:25]
	v_mfma_f32_16x16x32_bf16 v[14:17], v[168:171], v[230:233], v[14:17]
	v_mfma_f32_16x16x32_bf16 v[6:9], v[150:153], v[238:241], v[6:9]
	v_mfma_f32_16x16x32_bf16 v[2:5], v[168:171], v[238:241], v[2:5]
	s_barrier
	s_setprio 0
	s_add_i32 s83, s83, 2
	s_add_u32 s50, s50, 0x100
	s_addc_u32 s51, s51, 0
	s_add_u32 s79, s79, 0x100
	s_addc_u32 s81, s81, 0
	s_cmp_gt_u32 s83, 61
	s_cbranch_scc0 .LBB0_916
	s_and_b64 vcc, exec, s[16:17]
	s_cbranch_vccz .LBB0_919
	s_barrier

; #define PG8_STAGE(bufoff, gbase, voff) do { _Pragma("unroll") for (int _i = 0; _i < 2; ++_i) \
;         __builtin_amdgcn_global_load_lds((const unsigned*)((const char*)(gbase) + (voff)[_i]), (PG8_LAS unsigned*)(lds + (bufoff) + ldsw + _i * 8192), 16, 0, 0); } while (0)
; #define PG8_LDA(dst, b, h) do { _Pragma("unroll") for (int m = 0; m < 4; ++m) _Pragma("unroll") for (int k = 0; k < 2; ++k) dst[m][k] = *(const PG8_LAS bf16x8*)(lds + PG8_SA(b, h) + aoff + m * 2048 + k * 1024); } while (0)
; #define PG8_LDB(dst, b, h) do { _Pragma("unroll") for (int n = 0; n < 2; ++n) _Pragma("unroll") for (int k = 0; k < 2; ++k) dst[n][k] = *(const PG8_LAS bf16x8*)(lds + PG8_SB(b, h) + boff + n * 2048 + k * 1024); } while (0)
; #define PG8_WAIT_V(n) asm volatile("s_waitcnt vmcnt(" #n ")" ::: "memory")
; #define PG8_WAIT_L(n) asm volatile("s_waitcnt lgkmcnt(" #n ")" ::: "memory")
; #define PG8_BAR __builtin_amdgcn_s_barrier()
; #define PG8_SCHED __builtin_amdgcn_sched_barrier(0)
; template <class Epi, class Sched, bool ALIGN_EPI = false, bool SP2 = false, bool I8 = false, bool F16 = false>
; __device__ __forceinline__ void gemm_phase(PG8_LAS unsigned char* lds, const Gemm g, const Sched& S, const Epi& E) {
;     ...
;         for (int t = 0; t < nt; t += 2) {
;             const bool last = (t == nt - 2);
;             const char* a1 = cA + (size_t)(t + 1) * kstep;
;             const char* a2 = last ? nA : cA + (size_t)(t + 2) * kstep; const char* b2 = last ? nB : cB + (size_t)(t + 2) * kstep;
;             const char* a3 = a2 + kstep; const char* b3 = b2 + kstep;
;             if (last && has_next) S.a_ready(nxt);
;             if constexpr (SP2) {
;             PG8_LDB(B0, 0, 0); PG8_LDB(B1, 0, 1); PG8_SCHED; PG8_LDA(At, 0, 0); PG8_STAGE(PG8_SA(1, 1), a1 + hstep, voffA);
;             PG8_WAIT_V(8); PG8_WAIT_L(0); PG8_BAR; PG8_MMA(0, 0, At, B0); PG8_MMA(0, 1, At, B1); PG8_BAR; PG8_SCHED;
;             PG8_LDA(At, 0, 1); PG8_STAGE(PG8_SB(0, 0), b2, voffB); PG8_STAGE(PG8_SB(0, 1), b2 + hstep, voffB); PG8_STAGE(PG8_SA(0, 0), a2, voffA);
;             PG8_WAIT_V(8); PG8_WAIT_L(0); PG8_BAR; PG8_MMA(1, 0, At, B0); PG8_MMA(1, 1, At, B1); PG8_BAR; PG8_SCHED;
.LBB0_1057:
	s_add_u32 s30, s52, 0xfff80080
	s_addc_u32 s31, s53, -1
	s_add_i32 vcc_hi, 0, 0x10000
	s_cmp_eq_u32 vcc_lo, 28
	s_cselect_b32 s57, s45, s31
	s_cselect_b32 s56, s79, s30
	v_add_u32_e32 v148, vcc_hi, v149
	s_cselect_b32 s55, s43, s85
	s_cselect_b32 s54, s81, s83
	s_add_i32 s4, 0, 0x14000
	ds_read_b128 v[140:143], v148
	ds_read_b128 v[144:147], v148 offset:1024
	ds_read_b128 v[154:157], v148 offset:2048
	ds_read_b128 v[158:161], v148 offset:3072
	v_add_u32_e32 v148, s4, v149
	ds_read_b128 v[162:165], v148
	ds_read_b128 v[166:169], v148 offset:1024
	ds_read_b128 v[170:173], v148 offset:2048
	ds_read_b128 v[174:177], v148 offset:3072
	v_lshl_add_u64 v[150:151], s[52:53], 0, v[136:137]
	s_add_i32 m0, s59, 0xc000
	ds_read_b128 v[178:181], v153
	ds_read_b128 v[198:201], v153 offset:1024
	ds_read_b128 v[202:205], v153 offset:2048
	ds_read_b128 v[206:209], v153 offset:3072
	ds_read_b128 v[226:229], v153 offset:4096
	ds_read_b128 v[230:233], v153 offset:5120
	ds_read_b128 v[234:237], v153 offset:6144
	ds_read_b128 v[238:241], v153 offset:7168
	global_load_lds_dwordx4 v[150:151], off
	v_lshl_add_u64 v[150:151], s[52:53], 0, v[138:139]
	s_add_i32 m0, s59, 0xe000
	s_nop 0
	global_load_lds_dwordx4 v[150:151], off
	s_waitcnt vmcnt(8)
	s_waitcnt lgkmcnt(0)
	s_setprio 1
	s_barrier
	v_mfma_i32_16x16x64_i8 v[126:129], v[140:143], v[178:181], v[126:129]
	v_mfma_i32_16x16x64_i8 v[118:121], v[154:157], v[178:181], v[118:121]
	v_mfma_i32_16x16x64_i8 v[110:113], v[140:143], v[202:205], v[110:113]
	v_mfma_i32_16x16x64_i8 v[102:105], v[154:157], v[202:205], v[102:105]
	v_mfma_i32_16x16x64_i8 v[94:97], v[140:143], v[226:229], v[94:97]
	v_mfma_i32_16x16x64_i8 v[86:89], v[154:157], v[226:229], v[86:89]
	v_mfma_i32_16x16x64_i8 v[78:81], v[140:143], v[234:237], v[78:81]
	v_mfma_i32_16x16x64_i8 v[70:73], v[154:157], v[234:237], v[70:73]
	v_mfma_i32_16x16x64_i8 v[126:129], v[144:147], v[198:201], v[126:129]
	v_mfma_i32_16x16x64_i8 v[118:121], v[158:161], v[198:201], v[118:121]
	v_mfma_i32_16x16x64_i8 v[110:113], v[144:147], v[206:209], v[110:113]
	v_mfma_i32_16x16x64_i8 v[102:105], v[158:161], v[206:209], v[102:105]
	v_mfma_i32_16x16x64_i8 v[94:97], v[144:147], v[230:233], v[94:97]
	v_mfma_i32_16x16x64_i8 v[86:89], v[158:161], v[230:233], v[86:89]
	v_mfma_i32_16x16x64_i8 v[78:81], v[144:147], v[238:241], v[78:81]
	v_mfma_i32_16x16x64_i8 v[70:73], v[158:161], v[238:241], v[70:73]
	v_mfma_i32_16x16x64_i8 v[122:125], v[162:165], v[178:181], v[122:125]
	v_mfma_i32_16x16x64_i8 v[114:117], v[170:173], v[178:181], v[114:117]
	v_mfma_i32_16x16x64_i8 v[106:109], v[162:165], v[202:205], v[106:109]
	v_mfma_i32_16x16x64_i8 v[98:101], v[170:173], v[202:205], v[98:101]
	v_mfma_i32_16x16x64_i8 v[90:93], v[162:165], v[226:229], v[90:93]
	v_mfma_i32_16x16x64_i8 v[82:85], v[170:173], v[226:229], v[82:85]
	v_mfma_i32_16x16x64_i8 v[74:77], v[162:165], v[234:237], v[74:77]
	v_mfma_i32_16x16x64_i8 v[66:69], v[170:173], v[234:237], v[66:69]
	v_mfma_i32_16x16x64_i8 v[122:125], v[166:169], v[198:201], v[122:125]
	v_mfma_i32_16x16x64_i8 v[114:117], v[174:177], v[198:201], v[114:117]
	v_mfma_i32_16x16x64_i8 v[106:109], v[166:169], v[206:209], v[106:109]
	v_mfma_i32_16x16x64_i8 v[98:101], v[174:177], v[206:209], v[98:101]
	v_mfma_i32_16x16x64_i8 v[90:93], v[166:169], v[230:233], v[90:93]
	v_mfma_i32_16x16x64_i8 v[82:85], v[174:177], v[230:233], v[82:85]
	v_mfma_i32_16x16x64_i8 v[74:77], v[166:169], v[238:241], v[74:77]
	v_mfma_i32_16x16x64_i8 v[66:69], v[174:177], v[238:241], v[66:69]
	s_barrier
	s_setprio 0
	s_add_i32 s5, vcc_hi, s58
	v_lshl_add_u64 v[150:151], s[54:55], 0, v[182:183]
	s_mov_b32 m0, s5
	ds_read_b128 v[178:181], v153 offset:16384
	ds_read_b128 v[198:201], v153 offset:17408
	ds_read_b128 v[202:205], v153 offset:18432
	ds_read_b128 v[206:209], v153 offset:19456
	ds_read_b128 v[226:229], v153 offset:20480
	ds_read_b128 v[230:233], v153 offset:21504
	ds_read_b128 v[234:237], v153 offset:22528
	ds_read_b128 v[238:241], v153 offset:23552
	global_load_lds_dwordx4 v[150:151], off
	s_add_i32 m0, s5, 0x2000
	s_add_u32 s30, s54, 0x80000
	v_lshl_add_u64 v[210:211], s[54:55], 0, v[130:131]
	s_addc_u32 s31, s55, 0
	s_add_i32 s4, s4, s58
	global_load_lds_dwordx4 v[210:211], off
	v_lshl_add_u64 v[242:243], s[30:31], 0, v[182:183]
	s_mov_b32 m0, s4
	v_lshl_add_u64 v[244:245], s[56:57], 0, v[132:133]
	global_load_lds_dwordx4 v[242:243], off
	v_lshl_add_u64 v[242:243], s[30:31], 0, v[130:131]
	s_add_i32 m0, s4, 0x2000
	s_nop 0
	global_load_lds_dwordx4 v[242:243], off
	v_lshl_add_u64 v[242:243], s[56:57], 0, v[134:135]
	s_mov_b32 m0, s59
	s_nop 0
	global_load_lds_dwordx4 v[242:243], off
	s_mov_b32 m0, s62
	s_nop 0
	global_load_lds_dwordx4 v[244:245], off
	s_waitcnt vmcnt(8)
	s_waitcnt lgkmcnt(0)
	s_setprio 1
	s_barrier
; #define PG8_STAGE(bufoff, gbase, voff) do { _Pragma("unroll") for (int _i = 0; _i < 2; ++_i) \
;         __builtin_amdgcn_global_load_lds((const unsigned*)((const char*)(gbase) + (voff)[_i]), (PG8_LAS unsigned*)(lds + (bufoff) + ldsw + _i * 8192), 16, 0, 0); } while (0)
; #define PG8_LDA(dst, b, h) do { _Pragma("unroll") for (int m = 0; m < 4; ++m) _Pragma("unroll") for (int k = 0; k < 2; ++k) dst[m][k] = *(const PG8_LAS bf16x8*)(lds + PG8_SA(b, h) + aoff + m * 2048 + k * 1024); } while (0)
; #define PG8_LDB(dst, b, h) do { _Pragma("unroll") for (int n = 0; n < 2; ++n) _Pragma("unroll") for (int k = 0; k < 2; ++k) dst[n][k] = *(const PG8_LAS bf16x8*)(lds + PG8_SB(b, h) + boff + n * 2048 + k * 1024); } while (0)
; #define PG8_WAIT_V(n) asm volatile("s_waitcnt vmcnt(" #n ")" ::: "memory")
; #define PG8_WAIT_L(n) asm volatile("s_waitcnt lgkmcnt(" #n ")" ::: "memory")
; #define PG8_BAR __builtin_amdgcn_s_barrier()
; #define PG8_SCHED __builtin_amdgcn_sched_barrier(0)
; template <class Epi, class Sched, bool ALIGN_EPI = false, bool SP2 = false, bool I8 = false, bool F16 = false>
; __device__ __forceinline__ void gemm_phase(PG8_LAS unsigned char* lds, const Gemm g, const Sched& S, const Epi& E) {
;     ...
;             PG8_WAIT_V(8); PG8_WAIT_L(0); PG8_BAR; PG8_MMA(1, 0, At, B0); PG8_MMA(1, 1, At, B1); PG8_BAR; PG8_SCHED;
;             PG8_LDB(B0, 1, 0); PG8_LDB(B1, 1, 1); PG8_SCHED; PG8_LDA(At, 1, 0); PG8_STAGE(PG8_SA(0, 1), a2 + hstep, voffA);
;             PG8_WAIT_V(8); PG8_WAIT_L(0); PG8_BAR; PG8_MMA(0, 0, At, B0); PG8_MMA(0, 1, At, B1); PG8_BAR; PG8_SCHED;
	v_mfma_i32_16x16x64_i8 v[62:65], v[140:143], v[178:181], v[62:65]
	v_mfma_i32_16x16x64_i8 v[54:57], v[154:157], v[178:181], v[54:57]
	v_mfma_i32_16x16x64_i8 v[46:49], v[140:143], v[202:205], v[46:49]
	v_mfma_i32_16x16x64_i8 v[38:41], v[154:157], v[202:205], v[38:41]
	v_mfma_i32_16x16x64_i8 v[30:33], v[140:143], v[226:229], v[30:33]
	v_mfma_i32_16x16x64_i8 v[22:25], v[154:157], v[226:229], v[22:25]
	v_mfma_i32_16x16x64_i8 v[14:17], v[140:143], v[234:237], v[14:17]
	v_mfma_i32_16x16x64_i8 v[6:9], v[154:157], v[234:237], v[6:9]
	v_mfma_i32_16x16x64_i8 v[62:65], v[144:147], v[198:201], v[62:65]
	v_mfma_i32_16x16x64_i8 v[54:57], v[158:161], v[198:201], v[54:57]
	v_mfma_i32_16x16x64_i8 v[46:49], v[144:147], v[206:209], v[46:49]
	v_mfma_i32_16x16x64_i8 v[38:41], v[158:161], v[206:209], v[38:41]
	v_mfma_i32_16x16x64_i8 v[30:33], v[144:147], v[230:233], v[30:33]
	v_mfma_i32_16x16x64_i8 v[22:25], v[158:161], v[230:233], v[22:25]
	v_mfma_i32_16x16x64_i8 v[14:17], v[144:147], v[238:241], v[14:17]
	v_mfma_i32_16x16x64_i8 v[6:9], v[158:161], v[238:241], v[6:9]
	v_mfma_i32_16x16x64_i8 v[58:61], v[162:165], v[178:181], v[58:61]
	v_mfma_i32_16x16x64_i8 v[50:53], v[170:173], v[178:181], v[50:53]
	v_mfma_i32_16x16x64_i8 v[42:45], v[162:165], v[202:205], v[42:45]
	v_mfma_i32_16x16x64_i8 v[34:37], v[170:173], v[202:205], v[34:37]
	v_mfma_i32_16x16x64_i8 v[26:29], v[162:165], v[226:229], v[26:29]
	v_mfma_i32_16x16x64_i8 v[18:21], v[170:173], v[226:229], v[18:21]
	v_mfma_i32_16x16x64_i8 v[10:13], v[162:165], v[234:237], v[10:13]
	v_mfma_i32_16x16x64_i8 v[2:5], v[170:173], v[234:237], v[2:5]
	v_mfma_i32_16x16x64_i8 v[58:61], v[166:169], v[198:201], v[58:61]
	v_mfma_i32_16x16x64_i8 v[50:53], v[174:177], v[198:201], v[50:53]
	v_mfma_i32_16x16x64_i8 v[42:45], v[166:169], v[206:209], v[42:45]
	v_mfma_i32_16x16x64_i8 v[34:37], v[174:177], v[206:209], v[34:37]
	v_mfma_i32_16x16x64_i8 v[26:29], v[166:169], v[230:233], v[26:29]
	v_mfma_i32_16x16x64_i8 v[18:21], v[174:177], v[230:233], v[18:21]
	v_mfma_i32_16x16x64_i8 v[10:13], v[166:169], v[238:241], v[10:13]
	v_mfma_i32_16x16x64_i8 v[2:5], v[174:177], v[238:241], v[2:5]
	s_barrier
	s_setprio 0
	s_add_i32 s4, 0, 0x18000
	v_add_u32_e32 v148, s4, v149
	s_add_i32 s5, 0, 0x1c000
	ds_read_b128 v[140:143], v148
	ds_read_b128 v[144:147], v148 offset:1024
	ds_read_b128 v[154:157], v148 offset:2048
	ds_read_b128 v[158:161], v148 offset:3072
	v_add_u32_e32 v148, s5, v149
	ds_read_b128 v[162:165], v148
	ds_read_b128 v[166:169], v148 offset:1024
	ds_read_b128 v[170:173], v148 offset:2048
	ds_read_b128 v[174:177], v148 offset:3072
	s_add_u32 s30, s56, 0x80000
	s_addc_u32 s31, s57, 0
	s_mov_b32 m0, s64
	v_lshl_add_u64 v[246:247], s[30:31], 0, v[134:135]
	ds_read_b128 v[178:181], v153 offset:32768
	ds_read_b128 v[198:201], v153 offset:33792
	ds_read_b128 v[202:205], v153 offset:34816
	ds_read_b128 v[206:209], v153 offset:35840
	ds_read_b128 v[226:229], v153 offset:36864
	ds_read_b128 v[230:233], v153 offset:37888
	ds_read_b128 v[234:237], v153 offset:38912
	ds_read_b128 v[238:241], v153 offset:39936
	global_load_lds_dwordx4 v[246:247], off
	v_lshl_add_u64 v[246:247], s[30:31], 0, v[132:133]
	s_mov_b32 m0, s65
	s_nop 0
	global_load_lds_dwordx4 v[246:247], off
	s_waitcnt vmcnt(8)
	s_waitcnt lgkmcnt(0)
	s_setprio 1
	s_barrier
	v_mfma_i32_16x16x64_i8 v[126:129], v[140:143], v[178:181], v[126:129]
	v_mfma_i32_16x16x64_i8 v[118:121], v[154:157], v[178:181], v[118:121]
	v_mfma_i32_16x16x64_i8 v[110:113], v[140:143], v[202:205], v[110:113]
	v_mfma_i32_16x16x64_i8 v[102:105], v[154:157], v[202:205], v[102:105]
	v_mfma_i32_16x16x64_i8 v[94:97], v[140:143], v[226:229], v[94:97]
	v_mfma_i32_16x16x64_i8 v[86:89], v[154:157], v[226:229], v[86:89]
	v_mfma_i32_16x16x64_i8 v[78:81], v[140:143], v[234:237], v[78:81]
	v_mfma_i32_16x16x64_i8 v[70:73], v[154:157], v[234:237], v[70:73]
	v_mfma_i32_16x16x64_i8 v[126:129], v[144:147], v[198:201], v[126:129]
	v_mfma_i32_16x16x64_i8 v[118:121], v[158:161], v[198:201], v[118:121]
	v_mfma_i32_16x16x64_i8 v[110:113], v[144:147], v[206:209], v[110:113]
	v_mfma_i32_16x16x64_i8 v[102:105], v[158:161], v[206:209], v[102:105]
	v_mfma_i32_16x16x64_i8 v[94:97], v[144:147], v[230:233], v[94:97]
	v_mfma_i32_16x16x64_i8 v[86:89], v[158:161], v[230:233], v[86:89]
	v_mfma_i32_16x16x64_i8 v[78:81], v[144:147], v[238:241], v[78:81]
	v_mfma_i32_16x16x64_i8 v[70:73], v[158:161], v[238:241], v[70:73]
	v_mfma_i32_16x16x64_i8 v[122:125], v[162:165], v[178:181], v[122:125]
	v_mfma_i32_16x16x64_i8 v[114:117], v[170:173], v[178:181], v[114:117]
	v_mfma_i32_16x16x64_i8 v[106:109], v[162:165], v[202:205], v[106:109]
	v_mfma_i32_16x16x64_i8 v[98:101], v[170:173], v[202:205], v[98:101]
	v_mfma_i32_16x16x64_i8 v[90:93], v[162:165], v[226:229], v[90:93]
	v_mfma_i32_16x16x64_i8 v[82:85], v[170:173], v[226:229], v[82:85]
	v_mfma_i32_16x16x64_i8 v[74:77], v[162:165], v[234:237], v[74:77]
	v_mfma_i32_16x16x64_i8 v[66:69], v[170:173], v[234:237], v[66:69]
	v_mfma_i32_16x16x64_i8 v[122:125], v[166:169], v[198:201], v[122:125]
	v_mfma_i32_16x16x64_i8 v[114:117], v[174:177], v[198:201], v[114:117]
	v_mfma_i32_16x16x64_i8 v[106:109], v[166:169], v[206:209], v[106:109]
	v_mfma_i32_16x16x64_i8 v[98:101], v[174:177], v[206:209], v[98:101]
	v_mfma_i32_16x16x64_i8 v[90:93], v[166:169], v[230:233], v[90:93]
	v_mfma_i32_16x16x64_i8 v[82:85], v[174:177], v[230:233], v[82:85]
	v_mfma_i32_16x16x64_i8 v[74:77], v[166:169], v[238:241], v[74:77]
	v_mfma_i32_16x16x64_i8 v[66:69], v[174:177], v[238:241], v[66:69]
	s_barrier
; #define PG8_STAGE(bufoff, gbase, voff) do { _Pragma("unroll") for (int _i = 0; _i < 2; ++_i) \
;         __builtin_amdgcn_global_load_lds((const unsigned*)((const char*)(gbase) + (voff)[_i]), (PG8_LAS unsigned*)(lds + (bufoff) + ldsw + _i * 8192), 16, 0, 0); } while (0)
; #define PG8_LDA(dst, b, h) do { _Pragma("unroll") for (int m = 0; m < 4; ++m) _Pragma("unroll") for (int k = 0; k < 2; ++k) dst[m][k] = *(const PG8_LAS bf16x8*)(lds + PG8_SA(b, h) + aoff + m * 2048 + k * 1024); } while (0)
; #define PG8_WAIT_V(n) asm volatile("s_waitcnt vmcnt(" #n ")" ::: "memory")
; #define PG8_WAIT_L(n) asm volatile("s_waitcnt lgkmcnt(" #n ")" ::: "memory")
; #define PG8_BAR __builtin_amdgcn_s_barrier()
; #define PG8_SCHED __builtin_amdgcn_sched_barrier(0)
; template <class Epi, class Sched, bool ALIGN_EPI = false, bool SP2 = false, bool I8 = false, bool F16 = false>
; __device__ __forceinline__ void gemm_phase(PG8_LAS unsigned char* lds, const Gemm g, const Sched& S, const Epi& E) {
;     ...
;             PG8_LDA(At, 1, 1); PG8_STAGE(PG8_SB(1, 0), b3, voffB); PG8_STAGE(PG8_SB(1, 1), b3 + hstep, voffB); PG8_STAGE(PG8_SA(1, 0), a3, voffA);
;             PG8_WAIT_V(8); PG8_WAIT_L(0); PG8_BAR; PG8_MMA(1, 0, At, B0); PG8_MMA(1, 1, At, B1); PG8_BAR; PG8_SCHED;
;     ...
;         if constexpr (ALIGN_EPI) { if (wr == 0) PG8_BAR; }
	s_setprio 0
	s_add_i32 s4, s4, s58
	v_lshl_add_u64 v[150:151], v[150:151], 0, s[74:75]
	s_mov_b32 m0, s4
	ds_read_b128 v[178:181], v153 offset:49152
	ds_read_b128 v[198:201], v153 offset:50176
	ds_read_b128 v[202:205], v153 offset:51200
	ds_read_b128 v[206:209], v153 offset:52224
	ds_read_b128 v[226:229], v153 offset:53248
	ds_read_b128 v[230:233], v153 offset:54272
	ds_read_b128 v[234:237], v153 offset:55296
	ds_read_b128 v[238:241], v153 offset:56320
	global_load_lds_dwordx4 v[150:151], off
	s_add_i32 m0, s4, 0x2000
	s_add_u32 s30, s54, 0x80080
	v_lshl_add_u64 v[150:151], v[210:211], 0, s[74:75]
	s_addc_u32 s31, s55, 0
	s_add_i32 s4, s5, s58
	global_load_lds_dwordx4 v[150:151], off
	v_lshl_add_u64 v[150:151], s[30:31], 0, v[182:183]
	s_mov_b32 m0, s4
	s_nop 0
	global_load_lds_dwordx4 v[150:151], off
	v_lshl_add_u64 v[150:151], s[30:31], 0, v[130:131]
	s_add_i32 m0, s4, 0x2000
	s_nop 0
	global_load_lds_dwordx4 v[150:151], off
	v_lshl_add_u64 v[150:151], v[242:243], 0, s[74:75]
	s_mov_b32 m0, s66
	s_nop 0
	global_load_lds_dwordx4 v[150:151], off
	v_lshl_add_u64 v[150:151], v[244:245], 0, s[74:75]
	s_mov_b32 m0, s67
	s_nop 0
	global_load_lds_dwordx4 v[150:151], off
	s_waitcnt vmcnt(8)
	s_waitcnt lgkmcnt(0)
	s_setprio 1
	s_barrier
	v_mfma_i32_16x16x64_i8 v[62:65], v[140:143], v[178:181], v[62:65]
	v_mfma_i32_16x16x64_i8 v[54:57], v[154:157], v[178:181], v[54:57]
	v_mfma_i32_16x16x64_i8 v[46:49], v[140:143], v[202:205], v[46:49]
	v_mfma_i32_16x16x64_i8 v[38:41], v[154:157], v[202:205], v[38:41]
	v_mfma_i32_16x16x64_i8 v[30:33], v[140:143], v[226:229], v[30:33]
	v_mfma_i32_16x16x64_i8 v[22:25], v[154:157], v[226:229], v[22:25]
	v_mfma_i32_16x16x64_i8 v[14:17], v[140:143], v[234:237], v[14:17]
	v_mfma_i32_16x16x64_i8 v[6:9], v[154:157], v[234:237], v[6:9]
	v_mfma_i32_16x16x64_i8 v[62:65], v[144:147], v[198:201], v[62:65]
	v_mfma_i32_16x16x64_i8 v[54:57], v[158:161], v[198:201], v[54:57]
	v_mfma_i32_16x16x64_i8 v[46:49], v[144:147], v[206:209], v[46:49]
	v_mfma_i32_16x16x64_i8 v[38:41], v[158:161], v[206:209], v[38:41]
	v_mfma_i32_16x16x64_i8 v[30:33], v[144:147], v[230:233], v[30:33]
	v_mfma_i32_16x16x64_i8 v[22:25], v[158:161], v[230:233], v[22:25]
	v_mfma_i32_16x16x64_i8 v[14:17], v[144:147], v[238:241], v[14:17]
	v_mfma_i32_16x16x64_i8 v[6:9], v[158:161], v[238:241], v[6:9]
	v_mfma_i32_16x16x64_i8 v[58:61], v[162:165], v[178:181], v[58:61]
	v_mfma_i32_16x16x64_i8 v[50:53], v[170:173], v[178:181], v[50:53]
	v_mfma_i32_16x16x64_i8 v[42:45], v[162:165], v[202:205], v[42:45]
	v_mfma_i32_16x16x64_i8 v[34:37], v[170:173], v[202:205], v[34:37]
	v_mfma_i32_16x16x64_i8 v[26:29], v[162:165], v[226:229], v[26:29]
	v_mfma_i32_16x16x64_i8 v[18:21], v[170:173], v[226:229], v[18:21]
	v_mfma_i32_16x16x64_i8 v[10:13], v[162:165], v[234:237], v[10:13]
	v_mfma_i32_16x16x64_i8 v[2:5], v[170:173], v[234:237], v[2:5]
	v_mfma_i32_16x16x64_i8 v[58:61], v[166:169], v[198:201], v[58:61]
	v_mfma_i32_16x16x64_i8 v[50:53], v[174:177], v[198:201], v[50:53]
	v_mfma_i32_16x16x64_i8 v[42:45], v[166:169], v[206:209], v[42:45]
	v_mfma_i32_16x16x64_i8 v[34:37], v[174:177], v[206:209], v[34:37]
	v_mfma_i32_16x16x64_i8 v[26:29], v[166:169], v[230:233], v[26:29]
	v_mfma_i32_16x16x64_i8 v[18:21], v[174:177], v[230:233], v[18:21]
	v_mfma_i32_16x16x64_i8 v[10:13], v[166:169], v[238:241], v[10:13]
	v_mfma_i32_16x16x64_i8 v[2:5], v[174:177], v[238:241], v[2:5]
	s_barrier
	s_setprio 0
	s_add_i32 vcc_lo, vcc_lo, 2
	s_add_u32 s52, s52, 0x100
	s_addc_u32 s53, s53, 0
	s_add_u32 s83, s83, 0x100
	s_addc_u32 s85, s85, 0
	s_cmp_gt_u32 vcc_lo, 29
	s_cbranch_scc0 .LBB0_1057
	s_and_b64 vcc, exec, s[36:37]
	s_cbranch_vccz .LBB0_1060
	s_barrier

; #define PG8_STAGE(bufoff, gbase, voff) do { _Pragma("unroll") for (int _i = 0; _i < 2; ++_i) \
;         __builtin_amdgcn_global_load_lds((const unsigned*)((const char*)(gbase) + (voff)[_i]), (PG8_LAS unsigned*)(lds + (bufoff) + ldsw + _i * 8192), 16, 0, 0); } while (0)
; #define PG8_LDA(dst, b, h) do { _Pragma("unroll") for (int m = 0; m < 4; ++m) _Pragma("unroll") for (int k = 0; k < 2; ++k) dst[m][k] = *(const PG8_LAS bf16x8*)(lds + PG8_SA(b, h) + aoff + m * 2048 + k * 1024); } while (0)
; #define PG8_LDB(dst, b, h) do { _Pragma("unroll") for (int n = 0; n < 2; ++n) _Pragma("unroll") for (int k = 0; k < 2; ++k) dst[n][k] = *(const PG8_LAS bf16x8*)(lds + PG8_SB(b, h) + boff + n * 2048 + k * 1024); } while (0)
; #define PG8_WAIT_V(n) asm volatile("s_waitcnt vmcnt(" #n ")" ::: "memory")
; #define PG8_WAIT_L(n) asm volatile("s_waitcnt lgkmcnt(" #n ")" ::: "memory")
; #define PG8_BAR __builtin_amdgcn_s_barrier()
; #define PG8_SCHED __builtin_amdgcn_sched_barrier(0)
; template <class Epi, class Sched, bool ALIGN_EPI = false, bool SP2 = false, bool I8 = false, bool F16 = false>
; __device__ __forceinline__ void gemm_phase(PG8_LAS unsigned char* lds, const Gemm g, const Sched& S, const Epi& E) {
;     ...
;         for (int t = 0; t < nt; t += 2) {
;             const bool last = (t == nt - 2);
;             const char* a1 = cA + (size_t)(t + 1) * kstep;
;             const char* a2 = last ? nA : cA + (size_t)(t + 2) * kstep; const char* b2 = last ? nB : cB + (size_t)(t + 2) * kstep;
;             const char* a3 = a2 + kstep; const char* b3 = b2 + kstep;
;             if (last && has_next) S.a_ready(nxt);
;             if constexpr (SP2) {
;             PG8_LDB(B0, 0, 0); PG8_LDB(B1, 0, 1); PG8_SCHED; PG8_LDA(At, 0, 0); PG8_STAGE(PG8_SA(1, 1), a1 + hstep, voffA);
;             PG8_WAIT_V(8); PG8_WAIT_L(0); PG8_BAR; PG8_MMA(0, 0, At, B0); PG8_MMA(0, 1, At, B1); PG8_BAR; PG8_SCHED;
;             PG8_LDA(At, 0, 1); PG8_STAGE(PG8_SB(0, 0), b2, voffB); PG8_STAGE(PG8_SB(0, 1), b2 + hstep, voffB); PG8_STAGE(PG8_SA(0, 0), a2, voffA);
;             PG8_WAIT_V(8); PG8_WAIT_L(0); PG8_BAR; PG8_MMA(1, 0, At, B0); PG8_MMA(1, 1, At, B1); PG8_BAR; PG8_SCHED;
.LBB0_1200:
	s_add_u32 s54, s52, 0x100
	s_addc_u32 s55, s53, 0
	s_add_i32 s31, 0, 0x10000
	s_cmpk_eq_i32 s30, 0x52
	s_cselect_b32 s59, s7, s55
	s_cselect_b32 s58, s6, s54
	s_cselect_b32 s57, s51, vcc_hi
	s_cselect_b32 s56, s50, vcc_lo
	s_add_i32 s34, 0, 0x14000
	v_add_u32_e32 v152, s31, v156
	v_add_u32_e32 v159, s34, v156
	ds_read_b128 v[140:143], v152
	ds_read_b128 v[144:147], v152 offset:1024
	ds_read_b128 v[148:151], v152 offset:2048
	ds_read_b128 v[152:155], v152 offset:3072
	ds_read_b128 v[160:163], v159
	ds_read_b128 v[164:167], v159 offset:1024
	ds_read_b128 v[168:171], v159 offset:2048
	ds_read_b128 v[172:175], v159 offset:3072
	v_lshl_add_u64 v[180:181], s[52:53], 0, v[136:137]
	s_add_i32 m0, s64, 0xc000
	ds_read_b128 v[176:179], v158
	ds_read_b128 v[198:201], v158 offset:1024
	ds_read_b128 v[202:205], v158 offset:2048
	ds_read_b128 v[206:209], v158 offset:3072
	ds_read_b128 v[226:229], v158 offset:4096
	ds_read_b128 v[230:233], v158 offset:5120
	ds_read_b128 v[234:237], v158 offset:6144
	ds_read_b128 v[238:241], v158 offset:7168
	global_load_lds_dwordx4 v[180:181], off
	v_lshl_add_u64 v[180:181], s[52:53], 0, v[138:139]
	s_add_i32 m0, s64, 0xe000
	s_nop 0
	global_load_lds_dwordx4 v[180:181], off
	s_waitcnt vmcnt(8)
	s_waitcnt lgkmcnt(0)
	s_setprio 1
	s_barrier
	v_mfma_i32_16x16x64_i8 v[126:129], v[140:143], v[176:179], v[126:129]
	v_mfma_i32_16x16x64_i8 v[122:125], v[148:151], v[176:179], v[122:125]
	v_mfma_i32_16x16x64_i8 v[110:113], v[140:143], v[202:205], v[110:113]
	v_mfma_i32_16x16x64_i8 v[106:109], v[148:151], v[202:205], v[106:109]
	v_mfma_i32_16x16x64_i8 v[94:97], v[140:143], v[226:229], v[94:97]
	v_mfma_i32_16x16x64_i8 v[90:93], v[148:151], v[226:229], v[90:93]
	v_mfma_i32_16x16x64_i8 v[78:81], v[140:143], v[234:237], v[78:81]
	v_mfma_i32_16x16x64_i8 v[74:77], v[148:151], v[234:237], v[74:77]
	v_mfma_i32_16x16x64_i8 v[126:129], v[144:147], v[198:201], v[126:129]
	v_mfma_i32_16x16x64_i8 v[122:125], v[152:155], v[198:201], v[122:125]
	v_mfma_i32_16x16x64_i8 v[110:113], v[144:147], v[206:209], v[110:113]
	v_mfma_i32_16x16x64_i8 v[106:109], v[152:155], v[206:209], v[106:109]
	v_mfma_i32_16x16x64_i8 v[94:97], v[144:147], v[230:233], v[94:97]
	v_mfma_i32_16x16x64_i8 v[90:93], v[152:155], v[230:233], v[90:93]
	v_mfma_i32_16x16x64_i8 v[78:81], v[144:147], v[238:241], v[78:81]
	v_mfma_i32_16x16x64_i8 v[74:77], v[152:155], v[238:241], v[74:77]
	v_mfma_i32_16x16x64_i8 v[118:121], v[160:163], v[176:179], v[118:121]
	v_mfma_i32_16x16x64_i8 v[114:117], v[168:171], v[176:179], v[114:117]
	v_mfma_i32_16x16x64_i8 v[102:105], v[160:163], v[202:205], v[102:105]
	v_mfma_i32_16x16x64_i8 v[98:101], v[168:171], v[202:205], v[98:101]
	v_mfma_i32_16x16x64_i8 v[86:89], v[160:163], v[226:229], v[86:89]
	v_mfma_i32_16x16x64_i8 v[82:85], v[168:171], v[226:229], v[82:85]
	v_mfma_i32_16x16x64_i8 v[70:73], v[160:163], v[234:237], v[70:73]
	v_mfma_i32_16x16x64_i8 v[66:69], v[168:171], v[234:237], v[66:69]
	v_mfma_i32_16x16x64_i8 v[118:121], v[164:167], v[198:201], v[118:121]
	v_mfma_i32_16x16x64_i8 v[114:117], v[172:175], v[198:201], v[114:117]
	v_mfma_i32_16x16x64_i8 v[102:105], v[164:167], v[206:209], v[102:105]
	v_mfma_i32_16x16x64_i8 v[98:101], v[172:175], v[206:209], v[98:101]
	v_mfma_i32_16x16x64_i8 v[86:89], v[164:167], v[230:233], v[86:89]
	v_mfma_i32_16x16x64_i8 v[82:85], v[172:175], v[230:233], v[82:85]
	v_mfma_i32_16x16x64_i8 v[70:73], v[164:167], v[238:241], v[70:73]
	v_mfma_i32_16x16x64_i8 v[66:69], v[172:175], v[238:241], v[66:69]
	s_barrier
	s_setprio 0
	s_add_i32 s31, s31, s62
	v_lshl_add_u64 v[180:181], s[56:57], 0, v[182:183]
	s_mov_b32 m0, s31
	ds_read_b128 v[176:179], v158 offset:16384
	ds_read_b128 v[198:201], v158 offset:17408
	ds_read_b128 v[202:205], v158 offset:18432
	ds_read_b128 v[206:209], v158 offset:19456
	ds_read_b128 v[226:229], v158 offset:20480
	ds_read_b128 v[230:233], v158 offset:21504
	ds_read_b128 v[234:237], v158 offset:22528
	ds_read_b128 v[238:241], v158 offset:23552
	global_load_lds_dwordx4 v[180:181], off
	s_add_i32 m0, s31, 0x2000
	s_add_u32 s52, s56, 0x158000
	v_lshl_add_u64 v[210:211], s[56:57], 0, v[130:131]
	s_addc_u32 s53, s57, 0
	s_add_i32 s31, s34, s62
	global_load_lds_dwordx4 v[210:211], off
	v_lshl_add_u64 v[242:243], s[52:53], 0, v[182:183]
	s_mov_b32 m0, s31
	v_lshl_add_u64 v[244:245], s[58:59], 0, v[132:133]
	global_load_lds_dwordx4 v[242:243], off
	v_lshl_add_u64 v[242:243], s[52:53], 0, v[130:131]
	s_add_i32 m0, s31, 0x2000
	s_nop 0
	global_load_lds_dwordx4 v[242:243], off
	v_lshl_add_u64 v[242:243], s[58:59], 0, v[134:135]
	s_mov_b32 m0, s64
	s_nop 0
	global_load_lds_dwordx4 v[242:243], off
	s_mov_b32 m0, s65
	s_nop 0
	global_load_lds_dwordx4 v[244:245], off
	s_waitcnt vmcnt(8)
	s_waitcnt lgkmcnt(0)
	s_setprio 1
	s_barrier
; #define PG8_STAGE(bufoff, gbase, voff) do { _Pragma("unroll") for (int _i = 0; _i < 2; ++_i) \
;         __builtin_amdgcn_global_load_lds((const unsigned*)((const char*)(gbase) + (voff)[_i]), (PG8_LAS unsigned*)(lds + (bufoff) + ldsw + _i * 8192), 16, 0, 0); } while (0)
; #define PG8_LDA(dst, b, h) do { _Pragma("unroll") for (int m = 0; m < 4; ++m) _Pragma("unroll") for (int k = 0; k < 2; ++k) dst[m][k] = *(const PG8_LAS bf16x8*)(lds + PG8_SA(b, h) + aoff + m * 2048 + k * 1024); } while (0)
; #define PG8_LDB(dst, b, h) do { _Pragma("unroll") for (int n = 0; n < 2; ++n) _Pragma("unroll") for (int k = 0; k < 2; ++k) dst[n][k] = *(const PG8_LAS bf16x8*)(lds + PG8_SB(b, h) + boff + n * 2048 + k * 1024); } while (0)
; #define PG8_WAIT_V(n) asm volatile("s_waitcnt vmcnt(" #n ")" ::: "memory")
; #define PG8_WAIT_L(n) asm volatile("s_waitcnt lgkmcnt(" #n ")" ::: "memory")
; #define PG8_BAR __builtin_amdgcn_s_barrier()
; #define PG8_SCHED __builtin_amdgcn_sched_barrier(0)
; template <class Epi, class Sched, bool ALIGN_EPI = false, bool SP2 = false, bool I8 = false, bool F16 = false>
; __device__ __forceinline__ void gemm_phase(PG8_LAS unsigned char* lds, const Gemm g, const Sched& S, const Epi& E) {
;     ...
;             PG8_WAIT_V(8); PG8_WAIT_L(0); PG8_BAR; PG8_MMA(1, 0, At, B0); PG8_MMA(1, 1, At, B1); PG8_BAR; PG8_SCHED;
;             PG8_LDB(B0, 1, 0); PG8_LDB(B1, 1, 1); PG8_SCHED; PG8_LDA(At, 1, 0); PG8_STAGE(PG8_SA(0, 1), a2 + hstep, voffA);
;             PG8_WAIT_V(8); PG8_WAIT_L(0); PG8_BAR; PG8_MMA(0, 0, At, B0); PG8_MMA(0, 1, At, B1); PG8_BAR; PG8_SCHED;
	v_mfma_i32_16x16x64_i8 v[62:65], v[140:143], v[176:179], v[62:65]
	v_mfma_i32_16x16x64_i8 v[58:61], v[148:151], v[176:179], v[58:61]
	v_mfma_i32_16x16x64_i8 v[46:49], v[140:143], v[202:205], v[46:49]
	v_mfma_i32_16x16x64_i8 v[42:45], v[148:151], v[202:205], v[42:45]
	v_mfma_i32_16x16x64_i8 v[30:33], v[140:143], v[226:229], v[30:33]
	v_mfma_i32_16x16x64_i8 v[26:29], v[148:151], v[226:229], v[26:29]
	v_mfma_i32_16x16x64_i8 v[14:17], v[140:143], v[234:237], v[14:17]
	v_mfma_i32_16x16x64_i8 v[10:13], v[148:151], v[234:237], v[10:13]
	v_mfma_i32_16x16x64_i8 v[62:65], v[144:147], v[198:201], v[62:65]
	v_mfma_i32_16x16x64_i8 v[58:61], v[152:155], v[198:201], v[58:61]
	v_mfma_i32_16x16x64_i8 v[46:49], v[144:147], v[206:209], v[46:49]
	v_mfma_i32_16x16x64_i8 v[42:45], v[152:155], v[206:209], v[42:45]
	v_mfma_i32_16x16x64_i8 v[30:33], v[144:147], v[230:233], v[30:33]
	v_mfma_i32_16x16x64_i8 v[26:29], v[152:155], v[230:233], v[26:29]
	v_mfma_i32_16x16x64_i8 v[14:17], v[144:147], v[238:241], v[14:17]
	v_mfma_i32_16x16x64_i8 v[10:13], v[152:155], v[238:241], v[10:13]
	v_mfma_i32_16x16x64_i8 v[54:57], v[160:163], v[176:179], v[54:57]
	v_mfma_i32_16x16x64_i8 v[50:53], v[168:171], v[176:179], v[50:53]
	v_mfma_i32_16x16x64_i8 v[38:41], v[160:163], v[202:205], v[38:41]
	v_mfma_i32_16x16x64_i8 v[34:37], v[168:171], v[202:205], v[34:37]
	v_mfma_i32_16x16x64_i8 v[22:25], v[160:163], v[226:229], v[22:25]
	v_mfma_i32_16x16x64_i8 v[18:21], v[168:171], v[226:229], v[18:21]
	v_mfma_i32_16x16x64_i8 v[6:9], v[160:163], v[234:237], v[6:9]
	v_mfma_i32_16x16x64_i8 v[2:5], v[168:171], v[234:237], v[2:5]
	v_mfma_i32_16x16x64_i8 v[54:57], v[164:167], v[198:201], v[54:57]
	v_mfma_i32_16x16x64_i8 v[50:53], v[172:175], v[198:201], v[50:53]
	v_mfma_i32_16x16x64_i8 v[38:41], v[164:167], v[206:209], v[38:41]
	v_mfma_i32_16x16x64_i8 v[34:37], v[172:175], v[206:209], v[34:37]
	v_mfma_i32_16x16x64_i8 v[22:25], v[164:167], v[230:233], v[22:25]
	v_mfma_i32_16x16x64_i8 v[18:21], v[172:175], v[230:233], v[18:21]
	v_mfma_i32_16x16x64_i8 v[6:9], v[164:167], v[238:241], v[6:9]
	v_mfma_i32_16x16x64_i8 v[2:5], v[172:175], v[238:241], v[2:5]
	s_barrier
	s_setprio 0
	s_add_i32 s31, 0, 0x18000
	s_add_i32 s34, 0, 0x1c000
	v_add_u32_e32 v152, s31, v156
	v_add_u32_e32 v159, s34, v156
	ds_read_b128 v[140:143], v152
	ds_read_b128 v[144:147], v152 offset:1024
	ds_read_b128 v[148:151], v152 offset:2048
	ds_read_b128 v[152:155], v152 offset:3072
	ds_read_b128 v[160:163], v159
	ds_read_b128 v[164:167], v159 offset:1024
	ds_read_b128 v[168:171], v159 offset:2048
	ds_read_b128 v[172:175], v159 offset:3072
	s_add_u32 s52, s58, 0x158000
	s_addc_u32 s53, s59, 0
	s_mov_b32 m0, s66
	v_lshl_add_u64 v[246:247], s[52:53], 0, v[134:135]
	ds_read_b128 v[176:179], v158 offset:32768
	ds_read_b128 v[198:201], v158 offset:33792
	ds_read_b128 v[202:205], v158 offset:34816
	ds_read_b128 v[206:209], v158 offset:35840
	ds_read_b128 v[226:229], v158 offset:36864
	ds_read_b128 v[230:233], v158 offset:37888
	ds_read_b128 v[234:237], v158 offset:38912
	ds_read_b128 v[238:241], v158 offset:39936
	global_load_lds_dwordx4 v[246:247], off
	v_lshl_add_u64 v[246:247], s[52:53], 0, v[132:133]
	s_mov_b32 m0, s67
	s_nop 0
	global_load_lds_dwordx4 v[246:247], off
	s_waitcnt vmcnt(8)
	s_waitcnt lgkmcnt(0)
	s_setprio 1
	s_barrier
	v_mfma_i32_16x16x64_i8 v[126:129], v[140:143], v[176:179], v[126:129]
	v_mfma_i32_16x16x64_i8 v[122:125], v[148:151], v[176:179], v[122:125]
	v_mfma_i32_16x16x64_i8 v[110:113], v[140:143], v[202:205], v[110:113]
	v_mfma_i32_16x16x64_i8 v[106:109], v[148:151], v[202:205], v[106:109]
	v_mfma_i32_16x16x64_i8 v[94:97], v[140:143], v[226:229], v[94:97]
	v_mfma_i32_16x16x64_i8 v[90:93], v[148:151], v[226:229], v[90:93]
	v_mfma_i32_16x16x64_i8 v[78:81], v[140:143], v[234:237], v[78:81]
	v_mfma_i32_16x16x64_i8 v[74:77], v[148:151], v[234:237], v[74:77]
	v_mfma_i32_16x16x64_i8 v[126:129], v[144:147], v[198:201], v[126:129]
	v_mfma_i32_16x16x64_i8 v[122:125], v[152:155], v[198:201], v[122:125]
	v_mfma_i32_16x16x64_i8 v[110:113], v[144:147], v[206:209], v[110:113]
	v_mfma_i32_16x16x64_i8 v[106:109], v[152:155], v[206:209], v[106:109]
	v_mfma_i32_16x16x64_i8 v[94:97], v[144:147], v[230:233], v[94:97]
	v_mfma_i32_16x16x64_i8 v[90:93], v[152:155], v[230:233], v[90:93]
	v_mfma_i32_16x16x64_i8 v[78:81], v[144:147], v[238:241], v[78:81]
	v_mfma_i32_16x16x64_i8 v[74:77], v[152:155], v[238:241], v[74:77]
	v_mfma_i32_16x16x64_i8 v[118:121], v[160:163], v[176:179], v[118:121]
	v_mfma_i32_16x16x64_i8 v[114:117], v[168:171], v[176:179], v[114:117]
	v_mfma_i32_16x16x64_i8 v[102:105], v[160:163], v[202:205], v[102:105]
	v_mfma_i32_16x16x64_i8 v[98:101], v[168:171], v[202:205], v[98:101]
	v_mfma_i32_16x16x64_i8 v[86:89], v[160:163], v[226:229], v[86:89]
	v_mfma_i32_16x16x64_i8 v[82:85], v[168:171], v[226:229], v[82:85]
	v_mfma_i32_16x16x64_i8 v[70:73], v[160:163], v[234:237], v[70:73]
	v_mfma_i32_16x16x64_i8 v[66:69], v[168:171], v[234:237], v[66:69]
	v_mfma_i32_16x16x64_i8 v[118:121], v[164:167], v[198:201], v[118:121]
	v_mfma_i32_16x16x64_i8 v[114:117], v[172:175], v[198:201], v[114:117]
	v_mfma_i32_16x16x64_i8 v[102:105], v[164:167], v[206:209], v[102:105]
	v_mfma_i32_16x16x64_i8 v[98:101], v[172:175], v[206:209], v[98:101]
	v_mfma_i32_16x16x64_i8 v[86:89], v[164:167], v[230:233], v[86:89]
	v_mfma_i32_16x16x64_i8 v[82:85], v[172:175], v[230:233], v[82:85]
	v_mfma_i32_16x16x64_i8 v[70:73], v[164:167], v[238:241], v[70:73]
	v_mfma_i32_16x16x64_i8 v[66:69], v[172:175], v[238:241], v[66:69]
	s_barrier
; #define PG8_STAGE(bufoff, gbase, voff) do { _Pragma("unroll") for (int _i = 0; _i < 2; ++_i) \
;         __builtin_amdgcn_global_load_lds((const unsigned*)((const char*)(gbase) + (voff)[_i]), (PG8_LAS unsigned*)(lds + (bufoff) + ldsw + _i * 8192), 16, 0, 0); } while (0)
; #define PG8_LDA(dst, b, h) do { _Pragma("unroll") for (int m = 0; m < 4; ++m) _Pragma("unroll") for (int k = 0; k < 2; ++k) dst[m][k] = *(const PG8_LAS bf16x8*)(lds + PG8_SA(b, h) + aoff + m * 2048 + k * 1024); } while (0)
; #define PG8_WAIT_V(n) asm volatile("s_waitcnt vmcnt(" #n ")" ::: "memory")
; #define PG8_WAIT_L(n) asm volatile("s_waitcnt lgkmcnt(" #n ")" ::: "memory")
; #define PG8_BAR __builtin_amdgcn_s_barrier()
; #define PG8_SCHED __builtin_amdgcn_sched_barrier(0)
; template <class Epi, class Sched, bool ALIGN_EPI = false, bool SP2 = false, bool I8 = false, bool F16 = false>
; __device__ __forceinline__ void gemm_phase(PG8_LAS unsigned char* lds, const Gemm g, const Sched& S, const Epi& E) {
;     ...
;             PG8_LDA(At, 1, 1); PG8_STAGE(PG8_SB(1, 0), b3, voffB); PG8_STAGE(PG8_SB(1, 1), b3 + hstep, voffB); PG8_STAGE(PG8_SA(1, 0), a3, voffA);
;             PG8_WAIT_V(8); PG8_WAIT_L(0); PG8_BAR; PG8_MMA(1, 0, At, B0); PG8_MMA(1, 1, At, B1); PG8_BAR; PG8_SCHED;
;     ...
;         if constexpr (ALIGN_EPI) { if (wr == 0) PG8_BAR; }
	s_setprio 0
	s_add_i32 s31, s31, s62
	v_lshl_add_u64 v[180:181], v[180:181], 0, s[74:75]
	s_mov_b32 m0, s31
	ds_read_b128 v[176:179], v158 offset:49152
	ds_read_b128 v[198:201], v158 offset:50176
	ds_read_b128 v[202:205], v158 offset:51200
	ds_read_b128 v[206:209], v158 offset:52224
	ds_read_b128 v[226:229], v158 offset:53248
	ds_read_b128 v[230:233], v158 offset:54272
	ds_read_b128 v[234:237], v158 offset:55296
	ds_read_b128 v[238:241], v158 offset:56320
	global_load_lds_dwordx4 v[180:181], off
	s_add_i32 m0, s31, 0x2000
	s_add_u32 s52, s56, 0x158080
	v_lshl_add_u64 v[180:181], v[210:211], 0, s[74:75]
	s_addc_u32 s53, s57, 0
	s_add_i32 s31, s34, s62
	global_load_lds_dwordx4 v[180:181], off
	v_lshl_add_u64 v[180:181], s[52:53], 0, v[182:183]
	s_mov_b32 m0, s31
	s_nop 0
	global_load_lds_dwordx4 v[180:181], off
	v_lshl_add_u64 v[180:181], s[52:53], 0, v[130:131]
	s_add_i32 m0, s31, 0x2000
	s_nop 0
	global_load_lds_dwordx4 v[180:181], off
	v_lshl_add_u64 v[180:181], v[242:243], 0, s[74:75]
	s_mov_b32 m0, s68
	s_nop 0
	global_load_lds_dwordx4 v[180:181], off
	v_lshl_add_u64 v[180:181], v[244:245], 0, s[74:75]
	s_mov_b32 m0, s69
	s_nop 0
	global_load_lds_dwordx4 v[180:181], off
	s_waitcnt vmcnt(8)
	s_waitcnt lgkmcnt(0)
	s_setprio 1
	s_barrier
	v_mfma_i32_16x16x64_i8 v[62:65], v[140:143], v[176:179], v[62:65]
	v_mfma_i32_16x16x64_i8 v[58:61], v[148:151], v[176:179], v[58:61]
	v_mfma_i32_16x16x64_i8 v[46:49], v[140:143], v[202:205], v[46:49]
	v_mfma_i32_16x16x64_i8 v[42:45], v[148:151], v[202:205], v[42:45]
	v_mfma_i32_16x16x64_i8 v[30:33], v[140:143], v[226:229], v[30:33]
	v_mfma_i32_16x16x64_i8 v[26:29], v[148:151], v[226:229], v[26:29]
	v_mfma_i32_16x16x64_i8 v[14:17], v[140:143], v[234:237], v[14:17]
	v_mfma_i32_16x16x64_i8 v[10:13], v[148:151], v[234:237], v[10:13]
	v_mfma_i32_16x16x64_i8 v[62:65], v[144:147], v[198:201], v[62:65]
	v_mfma_i32_16x16x64_i8 v[58:61], v[152:155], v[198:201], v[58:61]
	v_mfma_i32_16x16x64_i8 v[46:49], v[144:147], v[206:209], v[46:49]
	v_mfma_i32_16x16x64_i8 v[42:45], v[152:155], v[206:209], v[42:45]
	v_mfma_i32_16x16x64_i8 v[30:33], v[144:147], v[230:233], v[30:33]
	v_mfma_i32_16x16x64_i8 v[26:29], v[152:155], v[230:233], v[26:29]
	v_mfma_i32_16x16x64_i8 v[14:17], v[144:147], v[238:241], v[14:17]
	v_mfma_i32_16x16x64_i8 v[10:13], v[152:155], v[238:241], v[10:13]
	v_mfma_i32_16x16x64_i8 v[54:57], v[160:163], v[176:179], v[54:57]
	v_mfma_i32_16x16x64_i8 v[50:53], v[168:171], v[176:179], v[50:53]
	v_mfma_i32_16x16x64_i8 v[38:41], v[160:163], v[202:205], v[38:41]
	v_mfma_i32_16x16x64_i8 v[34:37], v[168:171], v[202:205], v[34:37]
	v_mfma_i32_16x16x64_i8 v[22:25], v[160:163], v[226:229], v[22:25]
	v_mfma_i32_16x16x64_i8 v[18:21], v[168:171], v[226:229], v[18:21]
	v_mfma_i32_16x16x64_i8 v[6:9], v[160:163], v[234:237], v[6:9]
	v_mfma_i32_16x16x64_i8 v[2:5], v[168:171], v[234:237], v[2:5]
	v_mfma_i32_16x16x64_i8 v[54:57], v[164:167], v[198:201], v[54:57]
	v_mfma_i32_16x16x64_i8 v[50:53], v[172:175], v[198:201], v[50:53]
	v_mfma_i32_16x16x64_i8 v[38:41], v[164:167], v[206:209], v[38:41]
	v_mfma_i32_16x16x64_i8 v[34:37], v[172:175], v[206:209], v[34:37]
	v_mfma_i32_16x16x64_i8 v[22:25], v[164:167], v[230:233], v[22:25]
	v_mfma_i32_16x16x64_i8 v[18:21], v[172:175], v[230:233], v[18:21]
	v_mfma_i32_16x16x64_i8 v[6:9], v[164:167], v[238:241], v[6:9]
	v_mfma_i32_16x16x64_i8 v[2:5], v[172:175], v[238:241], v[2:5]
	s_barrier
	s_setprio 0
	s_add_i32 s30, s30, 2
	s_add_u32 vcc_lo, vcc_lo, 0x100
	s_addc_u32 vcc_hi, vcc_hi, 0
	s_cmpk_gt_u32 s30, 0x53
	s_mov_b64 s[52:53], s[54:55]
	s_cbranch_scc0 .LBB0_1200
	s_and_b64 vcc, exec, s[46:47]
	s_cbranch_vccz .LBB0_1203
	s_barrier
